# scan: y store moved into a DPP gap, staging poll with a short first check
# speedup vs baseline: 1.0061x; 1.0061x over previous
.Lsc_S_loop:
	s_waitcnt lgkmcnt(3)
	v_pk_fma_f32 v[10:11], v[80:81], v[30:31], v[16:17] op_sel_hi:[1,0,1] neg_lo:[0,1,0] neg_hi:[0,1,0]
	v_pk_fma_f32 v[8:9], v[82:83], v[30:31], v[18:19] op_sel_hi:[1,0,1] neg_lo:[0,1,0] neg_hi:[0,1,0]
	v_pk_mul_f32 v[24:25], v[10:11], v[84:85] op_sel:[0,0] op_sel_hi:[0,1]
	v_pk_fma_f32 v[24:25], v[10:11], v[86:87], v[24:25] op_sel:[1,0,0] op_sel_hi:[1,1,1]
	v_pk_fma_f32 v[24:25], v[8:9], v[88:89], v[24:25] op_sel:[0,0,0] op_sel_hi:[0,1,1]
	v_pk_fma_f32 v[24:25], v[8:9], v[90:91], v[24:25] op_sel:[1,0,0] op_sel_hi:[1,1,1]
	v_pk_fma_f32 v[16:17], v[92:93], v[156:157], v[10:11] op_sel:[0,1,0] op_sel_hi:[1,1,1]
	v_pk_fma_f32 v[18:19], v[94:95], v[156:157], v[8:9] op_sel:[0,1,0] op_sel_hi:[1,1,1]
	v_add_f32_dpp v15, v24, v24 row_ror:8 row_mask:0xf bank_mask:0xf bound_ctrl:1
	v_add_f32_dpp v32, v25, v25 row_ror:8 row_mask:0xf bank_mask:0xf bound_ctrl:1
	ds_read_b128 v[124:127], v34 offset:3072
	v_add_f32_dpp v15, v15, v15 row_ror:4 row_mask:0xf bank_mask:0xf bound_ctrl:1
	ds_read_b128 v[128:131], v34 offset:3328
	ds_read_b128 v[132:135], v34 offset:3584
	v_add_f32_dpp v15, v15, v15 row_ror:2 row_mask:0xf bank_mask:0xf bound_ctrl:1
	ds_read_b128 v[136:139], v34 offset:3840
	ds_read_b128 v[160:163], v35 offset:16
	v_add_f32_dpp v30, v15, v15 row_ror:1 row_mask:0xf bank_mask:0xf bound_ctrl:1
	v_pk_fma_f32 v[10:11], v[96:97], v[30:31], v[16:17] op_sel_hi:[1,0,1] neg_lo:[0,1,0] neg_hi:[0,1,0]
	v_pk_fma_f32 v[8:9], v[98:99], v[30:31], v[18:19] op_sel_hi:[1,0,1] neg_lo:[0,1,0] neg_hi:[0,1,0]
	v_pk_mul_f32 v[24:25], v[10:11], v[100:101] op_sel:[0,0] op_sel_hi:[0,1]
	v_pk_fma_f32 v[24:25], v[10:11], v[102:103], v[24:25] op_sel:[1,0,0] op_sel_hi:[1,1,1]
	v_pk_fma_f32 v[24:25], v[8:9], v[104:105], v[24:25] op_sel:[0,0,0] op_sel_hi:[0,1,1]
	v_pk_fma_f32 v[24:25], v[8:9], v[106:107], v[24:25] op_sel:[1,0,0] op_sel_hi:[1,1,1]
	v_pk_fma_f32 v[16:17], v[108:109], v[158:159], v[10:11] op_sel_hi:[1,0,1]
	v_pk_fma_f32 v[18:19], v[110:111], v[158:159], v[8:9] op_sel_hi:[1,0,1]
	v_add_f32_dpp v15, v24, v24 row_ror:8 row_mask:0xf bank_mask:0xf bound_ctrl:1
	v_add_f32_dpp v33, v25, v25 row_ror:8 row_mask:0xf bank_mask:0xf bound_ctrl:1
	ds_read_b128 v[76:79], v34 offset:4096
	v_add_f32_dpp v15, v15, v15 row_ror:4 row_mask:0xf bank_mask:0xf bound_ctrl:1
	ds_read_b128 v[80:83], v34 offset:4352
	ds_read_b128 v[84:87], v34 offset:4608
	v_add_f32_dpp v15, v15, v15 row_ror:2 row_mask:0xf bank_mask:0xf bound_ctrl:1
	ds_read_b128 v[88:91], v34 offset:4864
	ds_write2st64_b32 v37, v32, v33 offset0:0 offset1:2
	v_add_f32_dpp v30, v15, v15 row_ror:1 row_mask:0xf bank_mask:0xf bound_ctrl:1
	s_waitcnt lgkmcnt(4)
	v_pk_fma_f32 v[10:11], v[112:113], v[30:31], v[16:17] op_sel_hi:[1,0,1] neg_lo:[0,1,0] neg_hi:[0,1,0]
	v_pk_fma_f32 v[8:9], v[114:115], v[30:31], v[18:19] op_sel_hi:[1,0,1] neg_lo:[0,1,0] neg_hi:[0,1,0]
	v_pk_mul_f32 v[24:25], v[10:11], v[116:117] op_sel:[0,0] op_sel_hi:[0,1]
	v_pk_fma_f32 v[24:25], v[10:11], v[118:119], v[24:25] op_sel:[1,0,0] op_sel_hi:[1,1,1]
	v_pk_fma_f32 v[24:25], v[8:9], v[120:121], v[24:25] op_sel:[0,0,0] op_sel_hi:[0,1,1]
	v_pk_fma_f32 v[24:25], v[8:9], v[122:123], v[24:25] op_sel:[1,0,0] op_sel_hi:[1,1,1]
	v_pk_fma_f32 v[16:17], v[124:125], v[158:159], v[10:11] op_sel:[0,1,0] op_sel_hi:[1,1,1]
	v_pk_fma_f32 v[18:19], v[126:127], v[158:159], v[8:9] op_sel:[0,1,0] op_sel_hi:[1,1,1]
	v_add_f32_dpp v15, v24, v24 row_ror:8 row_mask:0xf bank_mask:0xf bound_ctrl:1
	v_add_f32_dpp v32, v25, v25 row_ror:8 row_mask:0xf bank_mask:0xf bound_ctrl:1
	ds_read_b128 v[92:95], v34 offset:5120
	v_add_f32_dpp v15, v15, v15 row_ror:4 row_mask:0xf bank_mask:0xf bound_ctrl:1
	ds_read_b128 v[96:99], v34 offset:5376
	ds_read_b128 v[100:103], v34 offset:5632
	v_add_f32_dpp v15, v15, v15 row_ror:2 row_mask:0xf bank_mask:0xf bound_ctrl:1
	ds_read_b128 v[104:107], v34 offset:5888
	s_nop 0
	v_add_f32_dpp v30, v15, v15 row_ror:1 row_mask:0xf bank_mask:0xf bound_ctrl:1
	v_pk_fma_f32 v[10:11], v[128:129], v[30:31], v[16:17] op_sel_hi:[1,0,1] neg_lo:[0,1,0] neg_hi:[0,1,0]
	v_pk_fma_f32 v[8:9], v[130:131], v[30:31], v[18:19] op_sel_hi:[1,0,1] neg_lo:[0,1,0] neg_hi:[0,1,0]
	v_pk_mul_f32 v[24:25], v[10:11], v[132:133] op_sel:[0,0] op_sel_hi:[0,1]
	v_pk_fma_f32 v[24:25], v[10:11], v[134:135], v[24:25] op_sel:[1,0,0] op_sel_hi:[1,1,1]
	v_pk_fma_f32 v[24:25], v[8:9], v[136:137], v[24:25] op_sel:[0,0,0] op_sel_hi:[0,1,1]
	v_pk_fma_f32 v[24:25], v[8:9], v[138:139], v[24:25] op_sel:[1,0,0] op_sel_hi:[1,1,1]
	v_pk_fma_f32 v[16:17], v[76:77], v[160:161], v[10:11] op_sel_hi:[1,0,1]
	v_pk_fma_f32 v[18:19], v[78:79], v[160:161], v[8:9] op_sel_hi:[1,0,1]
	v_add_f32_dpp v15, v24, v24 row_ror:8 row_mask:0xf bank_mask:0xf bound_ctrl:1
	v_add_f32_dpp v33, v25, v25 row_ror:8 row_mask:0xf bank_mask:0xf bound_ctrl:1
	ds_read_b128 v[108:111], v34 offset:6144
	v_add_f32_dpp v15, v15, v15 row_ror:4 row_mask:0xf bank_mask:0xf bound_ctrl:1
	ds_read_b128 v[112:115], v34 offset:6400
	ds_read_b128 v[116:119], v34 offset:6656
	v_add_f32_dpp v15, v15, v15 row_ror:2 row_mask:0xf bank_mask:0xf bound_ctrl:1
	ds_read_b128 v[120:123], v34 offset:6912
	ds_read_b128 v[140:143], v34 offset:33792
	ds_write2st64_b32 v37, v32, v33 offset0:4 offset1:6
	v_add_f32_dpp v30, v15, v15 row_ror:1 row_mask:0xf bank_mask:0xf bound_ctrl:1
	s_waitcnt lgkmcnt(5)
	v_pk_fma_f32 v[10:11], v[80:81], v[30:31], v[16:17] op_sel_hi:[1,0,1] neg_lo:[0,1,0] neg_hi:[0,1,0]
	v_pk_fma_f32 v[8:9], v[82:83], v[30:31], v[18:19] op_sel_hi:[1,0,1] neg_lo:[0,1,0] neg_hi:[0,1,0]
	v_pk_mul_f32 v[24:25], v[10:11], v[84:85] op_sel:[0,0] op_sel_hi:[0,1]
	v_pk_fma_f32 v[24:25], v[10:11], v[86:87], v[24:25] op_sel:[1,0,0] op_sel_hi:[1,1,1]
	v_pk_fma_f32 v[24:25], v[8:9], v[88:89], v[24:25] op_sel:[0,0,0] op_sel_hi:[0,1,1]
	v_pk_fma_f32 v[24:25], v[8:9], v[90:91], v[24:25] op_sel:[1,0,0] op_sel_hi:[1,1,1]
	v_pk_fma_f32 v[16:17], v[92:93], v[160:161], v[10:11] op_sel:[0,1,0] op_sel_hi:[1,1,1]
	v_pk_fma_f32 v[18:19], v[94:95], v[160:161], v[8:9] op_sel:[0,1,0] op_sel_hi:[1,1,1]
	v_add_f32_dpp v15, v24, v24 row_ror:8 row_mask:0xf bank_mask:0xf bound_ctrl:1
	v_add_f32_dpp v32, v25, v25 row_ror:8 row_mask:0xf bank_mask:0xf bound_ctrl:1
	ds_read_b128 v[124:127], v34 offset:7168
	v_add_f32_dpp v15, v15, v15 row_ror:4 row_mask:0xf bank_mask:0xf bound_ctrl:1
	ds_read_b128 v[128:131], v34 offset:7424
	ds_read_b128 v[132:135], v34 offset:7680
	v_add_f32_dpp v15, v15, v15 row_ror:2 row_mask:0xf bank_mask:0xf bound_ctrl:1
	ds_read_b128 v[136:139], v34 offset:7936
	ds_read_b128 v[156:159], v35 offset:32
	v_add_f32_dpp v30, v15, v15 row_ror:1 row_mask:0xf bank_mask:0xf bound_ctrl:1
	v_pk_fma_f32 v[10:11], v[96:97], v[30:31], v[16:17] op_sel_hi:[1,0,1] neg_lo:[0,1,0] neg_hi:[0,1,0]
	v_pk_fma_f32 v[8:9], v[98:99], v[30:31], v[18:19] op_sel_hi:[1,0,1] neg_lo:[0,1,0] neg_hi:[0,1,0]
	v_pk_mul_f32 v[24:25], v[10:11], v[100:101] op_sel:[0,0] op_sel_hi:[0,1]
	v_pk_fma_f32 v[24:25], v[10:11], v[102:103], v[24:25] op_sel:[1,0,0] op_sel_hi:[1,1,1]
	v_pk_fma_f32 v[24:25], v[8:9], v[104:105], v[24:25] op_sel:[0,0,0] op_sel_hi:[0,1,1]
	v_pk_fma_f32 v[24:25], v[8:9], v[106:107], v[24:25] op_sel:[1,0,0] op_sel_hi:[1,1,1]
	v_pk_fma_f32 v[16:17], v[108:109], v[162:163], v[10:11] op_sel_hi:[1,0,1]
	v_pk_fma_f32 v[18:19], v[110:111], v[162:163], v[8:9] op_sel_hi:[1,0,1]
	v_add_f32_dpp v15, v24, v24 row_ror:8 row_mask:0xf bank_mask:0xf bound_ctrl:1
	v_add_f32_dpp v33, v25, v25 row_ror:8 row_mask:0xf bank_mask:0xf bound_ctrl:1
	ds_read_b128 v[76:79], v34 offset:8192
	v_add_f32_dpp v15, v15, v15 row_ror:4 row_mask:0xf bank_mask:0xf bound_ctrl:1
	ds_read_b128 v[80:83], v34 offset:8448
	ds_read_b128 v[84:87], v34 offset:8704
	v_add_f32_dpp v15, v15, v15 row_ror:2 row_mask:0xf bank_mask:0xf bound_ctrl:1
	ds_read_b128 v[88:91], v34 offset:8960
	ds_read_b128 v[144:147], v34 offset:33024
	ds_write2st64_b32 v37, v32, v33 offset0:8 offset1:10
	v_add_f32_dpp v30, v15, v15 row_ror:1 row_mask:0xf bank_mask:0xf bound_ctrl:1
	s_waitcnt lgkmcnt(5)
	v_pk_fma_f32 v[10:11], v[112:113], v[30:31], v[16:17] op_sel_hi:[1,0,1] neg_lo:[0,1,0] neg_hi:[0,1,0]
	v_pk_fma_f32 v[8:9], v[114:115], v[30:31], v[18:19] op_sel_hi:[1,0,1] neg_lo:[0,1,0] neg_hi:[0,1,0]
	v_pk_mul_f32 v[24:25], v[10:11], v[116:117] op_sel:[0,0] op_sel_hi:[0,1]
	v_pk_fma_f32 v[24:25], v[10:11], v[118:119], v[24:25] op_sel:[1,0,0] op_sel_hi:[1,1,1]
	v_pk_fma_f32 v[24:25], v[8:9], v[120:121], v[24:25] op_sel:[0,0,0] op_sel_hi:[0,1,1]
	v_pk_fma_f32 v[24:25], v[8:9], v[122:123], v[24:25] op_sel:[1,0,0] op_sel_hi:[1,1,1]
	v_pk_fma_f32 v[16:17], v[124:125], v[162:163], v[10:11] op_sel:[0,1,0] op_sel_hi:[1,1,1]
	v_pk_fma_f32 v[18:19], v[126:127], v[162:163], v[8:9] op_sel:[0,1,0] op_sel_hi:[1,1,1]
	v_add_f32_dpp v15, v24, v24 row_ror:8 row_mask:0xf bank_mask:0xf bound_ctrl:1
	v_add_f32_dpp v32, v25, v25 row_ror:8 row_mask:0xf bank_mask:0xf bound_ctrl:1
	ds_read_b128 v[92:95], v34 offset:9216
	v_add_f32_dpp v15, v15, v15 row_ror:4 row_mask:0xf bank_mask:0xf bound_ctrl:1
	ds_read_b128 v[96:99], v34 offset:9472
	ds_read_b128 v[100:103], v34 offset:9728
	v_add_f32_dpp v15, v15, v15 row_ror:2 row_mask:0xf bank_mask:0xf bound_ctrl:1
	ds_read_b128 v[104:107], v34 offset:9984
	s_nop 0
	v_add_f32_dpp v30, v15, v15 row_ror:1 row_mask:0xf bank_mask:0xf bound_ctrl:1
	v_pk_fma_f32 v[10:11], v[128:129], v[30:31], v[16:17] op_sel_hi:[1,0,1] neg_lo:[0,1,0] neg_hi:[0,1,0]
	v_pk_fma_f32 v[8:9], v[130:131], v[30:31], v[18:19] op_sel_hi:[1,0,1] neg_lo:[0,1,0] neg_hi:[0,1,0]
	v_pk_mul_f32 v[24:25], v[10:11], v[132:133] op_sel:[0,0] op_sel_hi:[0,1]
	v_pk_fma_f32 v[24:25], v[10:11], v[134:135], v[24:25] op_sel:[1,0,0] op_sel_hi:[1,1,1]
	v_pk_fma_f32 v[24:25], v[8:9], v[136:137], v[24:25] op_sel:[0,0,0] op_sel_hi:[0,1,1]
	v_pk_fma_f32 v[24:25], v[8:9], v[138:139], v[24:25] op_sel:[1,0,0] op_sel_hi:[1,1,1]
	s_nop 1
	v_add_f32_dpp v33, v25, v25 row_ror:8 row_mask:0xf bank_mask:0xf bound_ctrl:1
	ds_write2st64_b32 v37, v32, v33 offset0:12 offset1:14
	v_pk_mul_f32 v[10:11], v[10:11], v[140:141]
	v_pk_mul_f32 v[8:9], v[8:9], v[142:143]
	s_waitcnt lgkmcnt(6)
	v_pk_mul_f32 v[24:25], v[10:11], v[144:145]
	v_pk_fma_f32 v[24:25], v[8:9], v[146:147], v[24:25]
	v_add_f32_e32 v24, v24, v25
	v_pk_fma_f32 v[16:17], v[76:77], v[156:157], v[10:11] op_sel_hi:[1,0,1]
	v_pk_fma_f32 v[18:19], v[78:79], v[156:157], v[8:9] op_sel_hi:[1,0,1]
	v_add_f32_dpp v15, v24, v24 row_ror:8 row_mask:0xf bank_mask:0xf bound_ctrl:1
	ds_read_b128 v[108:111], v34 offset:10240
	ds_read_b128 v[112:115], v34 offset:10496
	v_add_f32_dpp v15, v15, v15 row_ror:4 row_mask:0xf bank_mask:0xf bound_ctrl:1
	ds_read_b128 v[116:119], v34 offset:10752
	ds_read_b128 v[120:123], v34 offset:11008
	v_add_f32_dpp v15, v15, v15 row_ror:2 row_mask:0xf bank_mask:0xf bound_ctrl:1
	s_nop 1
	v_add_f32_dpp v30, v15, v15 row_ror:1 row_mask:0xf bank_mask:0xf bound_ctrl:1
	s_waitcnt lgkmcnt(3)
	v_pk_fma_f32 v[10:11], v[80:81], v[30:31], v[16:17] op_sel_hi:[1,0,1] neg_lo:[0,1,0] neg_hi:[0,1,0]
	v_pk_fma_f32 v[8:9], v[82:83], v[30:31], v[18:19] op_sel_hi:[1,0,1] neg_lo:[0,1,0] neg_hi:[0,1,0]
	v_pk_mul_f32 v[24:25], v[10:11], v[84:85] op_sel:[0,0] op_sel_hi:[0,1]
	v_pk_fma_f32 v[24:25], v[10:11], v[86:87], v[24:25] op_sel:[1,0,0] op_sel_hi:[1,1,1]
	v_pk_fma_f32 v[24:25], v[8:9], v[88:89], v[24:25] op_sel:[0,0,0] op_sel_hi:[0,1,1]
	v_pk_fma_f32 v[24:25], v[8:9], v[90:91], v[24:25] op_sel:[1,0,0] op_sel_hi:[1,1,1]
	v_pk_fma_f32 v[16:17], v[92:93], v[156:157], v[10:11] op_sel:[0,1,0] op_sel_hi:[1,1,1]
	v_pk_fma_f32 v[18:19], v[94:95], v[156:157], v[8:9] op_sel:[0,1,0] op_sel_hi:[1,1,1]
	v_add_f32_dpp v15, v24, v24 row_ror:8 row_mask:0xf bank_mask:0xf bound_ctrl:1
	v_add_f32_dpp v32, v25, v25 row_ror:8 row_mask:0xf bank_mask:0xf bound_ctrl:1
	ds_read_b128 v[124:127], v34 offset:11264
	v_add_f32_dpp v15, v15, v15 row_ror:4 row_mask:0xf bank_mask:0xf bound_ctrl:1
	ds_read_b128 v[128:131], v34 offset:11520
	ds_read_b128 v[132:135], v34 offset:11776
	v_add_f32_dpp v15, v15, v15 row_ror:2 row_mask:0xf bank_mask:0xf bound_ctrl:1
	ds_read_b128 v[136:139], v34 offset:12032
	ds_read_b128 v[160:163], v35 offset:48
	v_add_f32_dpp v30, v15, v15 row_ror:1 row_mask:0xf bank_mask:0xf bound_ctrl:1
	v_pk_fma_f32 v[10:11], v[96:97], v[30:31], v[16:17] op_sel_hi:[1,0,1] neg_lo:[0,1,0] neg_hi:[0,1,0]
	v_pk_fma_f32 v[8:9], v[98:99], v[30:31], v[18:19] op_sel_hi:[1,0,1] neg_lo:[0,1,0] neg_hi:[0,1,0]
	v_pk_mul_f32 v[24:25], v[10:11], v[100:101] op_sel:[0,0] op_sel_hi:[0,1]
	v_pk_fma_f32 v[24:25], v[10:11], v[102:103], v[24:25] op_sel:[1,0,0] op_sel_hi:[1,1,1]
	v_pk_fma_f32 v[24:25], v[8:9], v[104:105], v[24:25] op_sel:[0,0,0] op_sel_hi:[0,1,1]
	v_pk_fma_f32 v[24:25], v[8:9], v[106:107], v[24:25] op_sel:[1,0,0] op_sel_hi:[1,1,1]
	v_pk_fma_f32 v[16:17], v[108:109], v[158:159], v[10:11] op_sel_hi:[1,0,1]
	v_pk_fma_f32 v[18:19], v[110:111], v[158:159], v[8:9] op_sel_hi:[1,0,1]
	v_add_f32_dpp v15, v24, v24 row_ror:8 row_mask:0xf bank_mask:0xf bound_ctrl:1
	v_add_f32_dpp v33, v25, v25 row_ror:8 row_mask:0xf bank_mask:0xf bound_ctrl:1
	ds_read_b128 v[76:79], v34 offset:12288
	v_add_f32_dpp v15, v15, v15 row_ror:4 row_mask:0xf bank_mask:0xf bound_ctrl:1
	ds_read_b128 v[80:83], v34 offset:12544
	ds_read_b128 v[84:87], v34 offset:12800
	v_add_f32_dpp v15, v15, v15 row_ror:2 row_mask:0xf bank_mask:0xf bound_ctrl:1
	ds_read_b128 v[88:91], v34 offset:13056
	ds_write2st64_b32 v37, v32, v33 offset0:16 offset1:18
	v_add_f32_dpp v30, v15, v15 row_ror:1 row_mask:0xf bank_mask:0xf bound_ctrl:1
	s_waitcnt lgkmcnt(4)
	v_pk_fma_f32 v[10:11], v[112:113], v[30:31], v[16:17] op_sel_hi:[1,0,1] neg_lo:[0,1,0] neg_hi:[0,1,0]
	v_pk_fma_f32 v[8:9], v[114:115], v[30:31], v[18:19] op_sel_hi:[1,0,1] neg_lo:[0,1,0] neg_hi:[0,1,0]
	v_pk_mul_f32 v[24:25], v[10:11], v[116:117] op_sel:[0,0] op_sel_hi:[0,1]
	v_pk_fma_f32 v[24:25], v[10:11], v[118:119], v[24:25] op_sel:[1,0,0] op_sel_hi:[1,1,1]
	v_pk_fma_f32 v[24:25], v[8:9], v[120:121], v[24:25] op_sel:[0,0,0] op_sel_hi:[0,1,1]
	v_pk_fma_f32 v[24:25], v[8:9], v[122:123], v[24:25] op_sel:[1,0,0] op_sel_hi:[1,1,1]
	v_pk_fma_f32 v[16:17], v[124:125], v[158:159], v[10:11] op_sel:[0,1,0] op_sel_hi:[1,1,1]
	v_pk_fma_f32 v[18:19], v[126:127], v[158:159], v[8:9] op_sel:[0,1,0] op_sel_hi:[1,1,1]
	v_add_f32_dpp v15, v24, v24 row_ror:8 row_mask:0xf bank_mask:0xf bound_ctrl:1
	v_add_f32_dpp v32, v25, v25 row_ror:8 row_mask:0xf bank_mask:0xf bound_ctrl:1
	ds_read_b128 v[92:95], v34 offset:13312
	v_add_f32_dpp v15, v15, v15 row_ror:4 row_mask:0xf bank_mask:0xf bound_ctrl:1
	ds_read_b128 v[96:99], v34 offset:13568
	ds_read_b128 v[100:103], v34 offset:13824
	v_add_f32_dpp v15, v15, v15 row_ror:2 row_mask:0xf bank_mask:0xf bound_ctrl:1
	ds_read_b128 v[104:107], v34 offset:14080
	s_nop 0
	v_add_f32_dpp v30, v15, v15 row_ror:1 row_mask:0xf bank_mask:0xf bound_ctrl:1
	v_pk_fma_f32 v[10:11], v[128:129], v[30:31], v[16:17] op_sel_hi:[1,0,1] neg_lo:[0,1,0] neg_hi:[0,1,0]
	v_pk_fma_f32 v[8:9], v[130:131], v[30:31], v[18:19] op_sel_hi:[1,0,1] neg_lo:[0,1,0] neg_hi:[0,1,0]
	v_pk_mul_f32 v[24:25], v[10:11], v[132:133] op_sel:[0,0] op_sel_hi:[0,1]
	v_pk_fma_f32 v[24:25], v[10:11], v[134:135], v[24:25] op_sel:[1,0,0] op_sel_hi:[1,1,1]
	v_pk_fma_f32 v[24:25], v[8:9], v[136:137], v[24:25] op_sel:[0,0,0] op_sel_hi:[0,1,1]
	v_pk_fma_f32 v[24:25], v[8:9], v[138:139], v[24:25] op_sel:[1,0,0] op_sel_hi:[1,1,1]
	v_pk_fma_f32 v[16:17], v[76:77], v[160:161], v[10:11] op_sel_hi:[1,0,1]
	v_pk_fma_f32 v[18:19], v[78:79], v[160:161], v[8:9] op_sel_hi:[1,0,1]
	v_add_f32_dpp v15, v24, v24 row_ror:8 row_mask:0xf bank_mask:0xf bound_ctrl:1
	v_add_f32_dpp v33, v25, v25 row_ror:8 row_mask:0xf bank_mask:0xf bound_ctrl:1
	ds_read_b128 v[108:111], v34 offset:14336
	v_add_f32_dpp v15, v15, v15 row_ror:4 row_mask:0xf bank_mask:0xf bound_ctrl:1
	ds_read_b128 v[112:115], v34 offset:14592
	ds_read_b128 v[116:119], v34 offset:14848
	v_add_f32_dpp v15, v15, v15 row_ror:2 row_mask:0xf bank_mask:0xf bound_ctrl:1
	ds_read_b128 v[120:123], v34 offset:15104
	ds_read_b128 v[140:143], v34 offset:34048
	ds_write2st64_b32 v37, v32, v33 offset0:20 offset1:22
	v_add_f32_dpp v30, v15, v15 row_ror:1 row_mask:0xf bank_mask:0xf bound_ctrl:1
	s_waitcnt lgkmcnt(5)
	v_pk_fma_f32 v[10:11], v[80:81], v[30:31], v[16:17] op_sel_hi:[1,0,1] neg_lo:[0,1,0] neg_hi:[0,1,0]
	v_pk_fma_f32 v[8:9], v[82:83], v[30:31], v[18:19] op_sel_hi:[1,0,1] neg_lo:[0,1,0] neg_hi:[0,1,0]
	v_pk_mul_f32 v[24:25], v[10:11], v[84:85] op_sel:[0,0] op_sel_hi:[0,1]
	v_pk_fma_f32 v[24:25], v[10:11], v[86:87], v[24:25] op_sel:[1,0,0] op_sel_hi:[1,1,1]
	v_pk_fma_f32 v[24:25], v[8:9], v[88:89], v[24:25] op_sel:[0,0,0] op_sel_hi:[0,1,1]
	v_pk_fma_f32 v[24:25], v[8:9], v[90:91], v[24:25] op_sel:[1,0,0] op_sel_hi:[1,1,1]
	v_pk_fma_f32 v[16:17], v[92:93], v[160:161], v[10:11] op_sel:[0,1,0] op_sel_hi:[1,1,1]
	v_pk_fma_f32 v[18:19], v[94:95], v[160:161], v[8:9] op_sel:[0,1,0] op_sel_hi:[1,1,1]
	v_add_f32_dpp v15, v24, v24 row_ror:8 row_mask:0xf bank_mask:0xf bound_ctrl:1
	v_add_f32_dpp v32, v25, v25 row_ror:8 row_mask:0xf bank_mask:0xf bound_ctrl:1
	ds_read_b128 v[124:127], v34 offset:15360
	v_add_f32_dpp v15, v15, v15 row_ror:4 row_mask:0xf bank_mask:0xf bound_ctrl:1
	ds_read_b128 v[128:131], v34 offset:15616
	ds_read_b128 v[132:135], v34 offset:15872
	v_add_f32_dpp v15, v15, v15 row_ror:2 row_mask:0xf bank_mask:0xf bound_ctrl:1
	ds_read_b128 v[136:139], v34 offset:16128
	ds_read_b128 v[156:159], v35 offset:64
	v_add_f32_dpp v30, v15, v15 row_ror:1 row_mask:0xf bank_mask:0xf bound_ctrl:1
	v_pk_fma_f32 v[10:11], v[96:97], v[30:31], v[16:17] op_sel_hi:[1,0,1] neg_lo:[0,1,0] neg_hi:[0,1,0]
	v_pk_fma_f32 v[8:9], v[98:99], v[30:31], v[18:19] op_sel_hi:[1,0,1] neg_lo:[0,1,0] neg_hi:[0,1,0]
	v_pk_mul_f32 v[24:25], v[10:11], v[100:101] op_sel:[0,0] op_sel_hi:[0,1]
	v_pk_fma_f32 v[24:25], v[10:11], v[102:103], v[24:25] op_sel:[1,0,0] op_sel_hi:[1,1,1]
	v_pk_fma_f32 v[24:25], v[8:9], v[104:105], v[24:25] op_sel:[0,0,0] op_sel_hi:[0,1,1]
	v_pk_fma_f32 v[24:25], v[8:9], v[106:107], v[24:25] op_sel:[1,0,0] op_sel_hi:[1,1,1]
	v_pk_fma_f32 v[16:17], v[108:109], v[162:163], v[10:11] op_sel_hi:[1,0,1]
	v_pk_fma_f32 v[18:19], v[110:111], v[162:163], v[8:9] op_sel_hi:[1,0,1]
	v_add_f32_dpp v15, v24, v24 row_ror:8 row_mask:0xf bank_mask:0xf bound_ctrl:1
	v_add_f32_dpp v33, v25, v25 row_ror:8 row_mask:0xf bank_mask:0xf bound_ctrl:1
	ds_read_b128 v[76:79], v34 offset:16384
	v_add_f32_dpp v15, v15, v15 row_ror:4 row_mask:0xf bank_mask:0xf bound_ctrl:1
	ds_read_b128 v[80:83], v34 offset:16640
	ds_read_b128 v[84:87], v34 offset:16896
	v_add_f32_dpp v15, v15, v15 row_ror:2 row_mask:0xf bank_mask:0xf bound_ctrl:1
	ds_read_b128 v[88:91], v34 offset:17152
	ds_read_b128 v[144:147], v34 offset:33280
	ds_write2st64_b32 v37, v32, v33 offset0:24 offset1:26
	v_add_f32_dpp v30, v15, v15 row_ror:1 row_mask:0xf bank_mask:0xf bound_ctrl:1
	s_waitcnt lgkmcnt(5)
	v_pk_fma_f32 v[10:11], v[112:113], v[30:31], v[16:17] op_sel_hi:[1,0,1] neg_lo:[0,1,0] neg_hi:[0,1,0]
	v_pk_fma_f32 v[8:9], v[114:115], v[30:31], v[18:19] op_sel_hi:[1,0,1] neg_lo:[0,1,0] neg_hi:[0,1,0]
	v_pk_mul_f32 v[24:25], v[10:11], v[116:117] op_sel:[0,0] op_sel_hi:[0,1]
	v_pk_fma_f32 v[24:25], v[10:11], v[118:119], v[24:25] op_sel:[1,0,0] op_sel_hi:[1,1,1]
	v_pk_fma_f32 v[24:25], v[8:9], v[120:121], v[24:25] op_sel:[0,0,0] op_sel_hi:[0,1,1]
	v_pk_fma_f32 v[24:25], v[8:9], v[122:123], v[24:25] op_sel:[1,0,0] op_sel_hi:[1,1,1]
	v_pk_fma_f32 v[16:17], v[124:125], v[162:163], v[10:11] op_sel:[0,1,0] op_sel_hi:[1,1,1]
	v_pk_fma_f32 v[18:19], v[126:127], v[162:163], v[8:9] op_sel:[0,1,0] op_sel_hi:[1,1,1]
	v_add_f32_dpp v15, v24, v24 row_ror:8 row_mask:0xf bank_mask:0xf bound_ctrl:1
	v_add_f32_dpp v32, v25, v25 row_ror:8 row_mask:0xf bank_mask:0xf bound_ctrl:1
	ds_read_b128 v[92:95], v34 offset:17408
	v_add_f32_dpp v15, v15, v15 row_ror:4 row_mask:0xf bank_mask:0xf bound_ctrl:1
	ds_read_b128 v[96:99], v34 offset:17664
	ds_read_b128 v[100:103], v34 offset:17920
	v_add_f32_dpp v15, v15, v15 row_ror:2 row_mask:0xf bank_mask:0xf bound_ctrl:1
	ds_read_b128 v[104:107], v34 offset:18176
	s_nop 0
	v_add_f32_dpp v30, v15, v15 row_ror:1 row_mask:0xf bank_mask:0xf bound_ctrl:1
	v_pk_fma_f32 v[10:11], v[128:129], v[30:31], v[16:17] op_sel_hi:[1,0,1] neg_lo:[0,1,0] neg_hi:[0,1,0]
	v_pk_fma_f32 v[8:9], v[130:131], v[30:31], v[18:19] op_sel_hi:[1,0,1] neg_lo:[0,1,0] neg_hi:[0,1,0]
	v_pk_mul_f32 v[24:25], v[10:11], v[132:133] op_sel:[0,0] op_sel_hi:[0,1]
	v_pk_fma_f32 v[24:25], v[10:11], v[134:135], v[24:25] op_sel:[1,0,0] op_sel_hi:[1,1,1]
	v_pk_fma_f32 v[24:25], v[8:9], v[136:137], v[24:25] op_sel:[0,0,0] op_sel_hi:[0,1,1]
	v_pk_fma_f32 v[24:25], v[8:9], v[138:139], v[24:25] op_sel:[1,0,0] op_sel_hi:[1,1,1]
	s_nop 1
	v_add_f32_dpp v33, v25, v25 row_ror:8 row_mask:0xf bank_mask:0xf bound_ctrl:1
	ds_write2st64_b32 v37, v32, v33 offset0:28 offset1:30
	v_pk_mul_f32 v[10:11], v[10:11], v[140:141]
	v_pk_mul_f32 v[8:9], v[8:9], v[142:143]
	s_waitcnt lgkmcnt(6)
	v_pk_mul_f32 v[24:25], v[10:11], v[144:145]
	v_pk_fma_f32 v[24:25], v[8:9], v[146:147], v[24:25]
	v_add_f32_e32 v24, v24, v25
	v_pk_fma_f32 v[16:17], v[76:77], v[156:157], v[10:11] op_sel_hi:[1,0,1]
	v_pk_fma_f32 v[18:19], v[78:79], v[156:157], v[8:9] op_sel_hi:[1,0,1]
	v_add_f32_dpp v15, v24, v24 row_ror:8 row_mask:0xf bank_mask:0xf bound_ctrl:1
	ds_read_b128 v[108:111], v34 offset:18432
	ds_read_b128 v[112:115], v34 offset:18688
	v_add_f32_dpp v15, v15, v15 row_ror:4 row_mask:0xf bank_mask:0xf bound_ctrl:1
	ds_read_b128 v[116:119], v34 offset:18944
	ds_read_b128 v[120:123], v34 offset:19200
	v_add_f32_dpp v15, v15, v15 row_ror:2 row_mask:0xf bank_mask:0xf bound_ctrl:1
	s_nop 1
	v_add_f32_dpp v30, v15, v15 row_ror:1 row_mask:0xf bank_mask:0xf bound_ctrl:1
	s_waitcnt lgkmcnt(3)
	v_pk_fma_f32 v[10:11], v[80:81], v[30:31], v[16:17] op_sel_hi:[1,0,1] neg_lo:[0,1,0] neg_hi:[0,1,0]
	v_pk_fma_f32 v[8:9], v[82:83], v[30:31], v[18:19] op_sel_hi:[1,0,1] neg_lo:[0,1,0] neg_hi:[0,1,0]
	v_pk_mul_f32 v[24:25], v[10:11], v[84:85] op_sel:[0,0] op_sel_hi:[0,1]
	v_pk_fma_f32 v[24:25], v[10:11], v[86:87], v[24:25] op_sel:[1,0,0] op_sel_hi:[1,1,1]
	v_pk_fma_f32 v[24:25], v[8:9], v[88:89], v[24:25] op_sel:[0,0,0] op_sel_hi:[0,1,1]
	v_pk_fma_f32 v[24:25], v[8:9], v[90:91], v[24:25] op_sel:[1,0,0] op_sel_hi:[1,1,1]
	v_pk_fma_f32 v[16:17], v[92:93], v[156:157], v[10:11] op_sel:[0,1,0] op_sel_hi:[1,1,1]
	v_pk_fma_f32 v[18:19], v[94:95], v[156:157], v[8:9] op_sel:[0,1,0] op_sel_hi:[1,1,1]
	v_add_f32_dpp v15, v24, v24 row_ror:8 row_mask:0xf bank_mask:0xf bound_ctrl:1
	v_add_f32_dpp v32, v25, v25 row_ror:8 row_mask:0xf bank_mask:0xf bound_ctrl:1
	ds_read_b128 v[124:127], v34 offset:19456
	v_add_f32_dpp v15, v15, v15 row_ror:4 row_mask:0xf bank_mask:0xf bound_ctrl:1
	ds_read_b128 v[128:131], v34 offset:19712
	ds_read_b128 v[132:135], v34 offset:19968
	v_add_f32_dpp v15, v15, v15 row_ror:2 row_mask:0xf bank_mask:0xf bound_ctrl:1
	ds_read_b128 v[136:139], v34 offset:20224
	ds_read_b128 v[160:163], v35 offset:80
	v_add_f32_dpp v30, v15, v15 row_ror:1 row_mask:0xf bank_mask:0xf bound_ctrl:1
	v_pk_fma_f32 v[10:11], v[96:97], v[30:31], v[16:17] op_sel_hi:[1,0,1] neg_lo:[0,1,0] neg_hi:[0,1,0]
	v_pk_fma_f32 v[8:9], v[98:99], v[30:31], v[18:19] op_sel_hi:[1,0,1] neg_lo:[0,1,0] neg_hi:[0,1,0]
	v_pk_mul_f32 v[24:25], v[10:11], v[100:101] op_sel:[0,0] op_sel_hi:[0,1]
	v_pk_fma_f32 v[24:25], v[10:11], v[102:103], v[24:25] op_sel:[1,0,0] op_sel_hi:[1,1,1]
	v_pk_fma_f32 v[24:25], v[8:9], v[104:105], v[24:25] op_sel:[0,0,0] op_sel_hi:[0,1,1]
	v_pk_fma_f32 v[24:25], v[8:9], v[106:107], v[24:25] op_sel:[1,0,0] op_sel_hi:[1,1,1]
	v_pk_fma_f32 v[16:17], v[108:109], v[158:159], v[10:11] op_sel_hi:[1,0,1]
	v_pk_fma_f32 v[18:19], v[110:111], v[158:159], v[8:9] op_sel_hi:[1,0,1]
	v_add_f32_dpp v15, v24, v24 row_ror:8 row_mask:0xf bank_mask:0xf bound_ctrl:1
	v_add_f32_dpp v33, v25, v25 row_ror:8 row_mask:0xf bank_mask:0xf bound_ctrl:1
	ds_read_b128 v[76:79], v34 offset:20480
	v_add_f32_dpp v15, v15, v15 row_ror:4 row_mask:0xf bank_mask:0xf bound_ctrl:1
	ds_read_b128 v[80:83], v34 offset:20736
	ds_read_b128 v[84:87], v34 offset:20992
	v_add_f32_dpp v15, v15, v15 row_ror:2 row_mask:0xf bank_mask:0xf bound_ctrl:1
	ds_read_b128 v[88:91], v34 offset:21248
	ds_write2st64_b32 v37, v32, v33 offset0:32 offset1:34
	v_add_f32_dpp v30, v15, v15 row_ror:1 row_mask:0xf bank_mask:0xf bound_ctrl:1
	s_waitcnt lgkmcnt(4)
	v_pk_fma_f32 v[10:11], v[112:113], v[30:31], v[16:17] op_sel_hi:[1,0,1] neg_lo:[0,1,0] neg_hi:[0,1,0]
	v_pk_fma_f32 v[8:9], v[114:115], v[30:31], v[18:19] op_sel_hi:[1,0,1] neg_lo:[0,1,0] neg_hi:[0,1,0]
	v_pk_mul_f32 v[24:25], v[10:11], v[116:117] op_sel:[0,0] op_sel_hi:[0,1]
	v_pk_fma_f32 v[24:25], v[10:11], v[118:119], v[24:25] op_sel:[1,0,0] op_sel_hi:[1,1,1]
	v_pk_fma_f32 v[24:25], v[8:9], v[120:121], v[24:25] op_sel:[0,0,0] op_sel_hi:[0,1,1]
	v_pk_fma_f32 v[24:25], v[8:9], v[122:123], v[24:25] op_sel:[1,0,0] op_sel_hi:[1,1,1]
	v_pk_fma_f32 v[16:17], v[124:125], v[158:159], v[10:11] op_sel:[0,1,0] op_sel_hi:[1,1,1]
	v_pk_fma_f32 v[18:19], v[126:127], v[158:159], v[8:9] op_sel:[0,1,0] op_sel_hi:[1,1,1]
	v_add_f32_dpp v15, v24, v24 row_ror:8 row_mask:0xf bank_mask:0xf bound_ctrl:1
	v_add_f32_dpp v32, v25, v25 row_ror:8 row_mask:0xf bank_mask:0xf bound_ctrl:1
	ds_read_b128 v[92:95], v34 offset:21504
	v_add_f32_dpp v15, v15, v15 row_ror:4 row_mask:0xf bank_mask:0xf bound_ctrl:1
	ds_read_b128 v[96:99], v34 offset:21760
	ds_read_b128 v[100:103], v34 offset:22016
	v_add_f32_dpp v15, v15, v15 row_ror:2 row_mask:0xf bank_mask:0xf bound_ctrl:1
	ds_read_b128 v[104:107], v34 offset:22272
	s_nop 0
	v_add_f32_dpp v30, v15, v15 row_ror:1 row_mask:0xf bank_mask:0xf bound_ctrl:1
	v_pk_fma_f32 v[10:11], v[128:129], v[30:31], v[16:17] op_sel_hi:[1,0,1] neg_lo:[0,1,0] neg_hi:[0,1,0]
	v_pk_fma_f32 v[8:9], v[130:131], v[30:31], v[18:19] op_sel_hi:[1,0,1] neg_lo:[0,1,0] neg_hi:[0,1,0]
	v_pk_mul_f32 v[24:25], v[10:11], v[132:133] op_sel:[0,0] op_sel_hi:[0,1]
	v_pk_fma_f32 v[24:25], v[10:11], v[134:135], v[24:25] op_sel:[1,0,0] op_sel_hi:[1,1,1]
	v_pk_fma_f32 v[24:25], v[8:9], v[136:137], v[24:25] op_sel:[0,0,0] op_sel_hi:[0,1,1]
	v_pk_fma_f32 v[24:25], v[8:9], v[138:139], v[24:25] op_sel:[1,0,0] op_sel_hi:[1,1,1]
	v_pk_fma_f32 v[16:17], v[76:77], v[160:161], v[10:11] op_sel_hi:[1,0,1]
	v_pk_fma_f32 v[18:19], v[78:79], v[160:161], v[8:9] op_sel_hi:[1,0,1]
	v_add_f32_dpp v15, v24, v24 row_ror:8 row_mask:0xf bank_mask:0xf bound_ctrl:1
	v_add_f32_dpp v33, v25, v25 row_ror:8 row_mask:0xf bank_mask:0xf bound_ctrl:1
	ds_read_b128 v[108:111], v34 offset:22528
	v_add_f32_dpp v15, v15, v15 row_ror:4 row_mask:0xf bank_mask:0xf bound_ctrl:1
	ds_read_b128 v[112:115], v34 offset:22784
	ds_read_b128 v[116:119], v34 offset:23040
	v_add_f32_dpp v15, v15, v15 row_ror:2 row_mask:0xf bank_mask:0xf bound_ctrl:1
	ds_read_b128 v[120:123], v34 offset:23296
	ds_read_b128 v[140:143], v34 offset:34304
	ds_write2st64_b32 v37, v32, v33 offset0:36 offset1:38
	v_add_f32_dpp v30, v15, v15 row_ror:1 row_mask:0xf bank_mask:0xf bound_ctrl:1
	s_waitcnt lgkmcnt(5)
	v_pk_fma_f32 v[10:11], v[80:81], v[30:31], v[16:17] op_sel_hi:[1,0,1] neg_lo:[0,1,0] neg_hi:[0,1,0]
	v_pk_fma_f32 v[8:9], v[82:83], v[30:31], v[18:19] op_sel_hi:[1,0,1] neg_lo:[0,1,0] neg_hi:[0,1,0]
	v_pk_mul_f32 v[24:25], v[10:11], v[84:85] op_sel:[0,0] op_sel_hi:[0,1]
	v_pk_fma_f32 v[24:25], v[10:11], v[86:87], v[24:25] op_sel:[1,0,0] op_sel_hi:[1,1,1]
	v_pk_fma_f32 v[24:25], v[8:9], v[88:89], v[24:25] op_sel:[0,0,0] op_sel_hi:[0,1,1]
	v_pk_fma_f32 v[24:25], v[8:9], v[90:91], v[24:25] op_sel:[1,0,0] op_sel_hi:[1,1,1]
	v_pk_fma_f32 v[16:17], v[92:93], v[160:161], v[10:11] op_sel:[0,1,0] op_sel_hi:[1,1,1]
	v_pk_fma_f32 v[18:19], v[94:95], v[160:161], v[8:9] op_sel:[0,1,0] op_sel_hi:[1,1,1]
	v_add_f32_dpp v15, v24, v24 row_ror:8 row_mask:0xf bank_mask:0xf bound_ctrl:1
	v_add_f32_dpp v32, v25, v25 row_ror:8 row_mask:0xf bank_mask:0xf bound_ctrl:1
	ds_read_b128 v[124:127], v34 offset:23552
	v_add_f32_dpp v15, v15, v15 row_ror:4 row_mask:0xf bank_mask:0xf bound_ctrl:1
	ds_read_b128 v[128:131], v34 offset:23808
	ds_read_b128 v[132:135], v34 offset:24064
	v_add_f32_dpp v15, v15, v15 row_ror:2 row_mask:0xf bank_mask:0xf bound_ctrl:1
	ds_read_b128 v[136:139], v34 offset:24320
	ds_read_b128 v[156:159], v35 offset:96
	v_add_f32_dpp v30, v15, v15 row_ror:1 row_mask:0xf bank_mask:0xf bound_ctrl:1
	v_pk_fma_f32 v[10:11], v[96:97], v[30:31], v[16:17] op_sel_hi:[1,0,1] neg_lo:[0,1,0] neg_hi:[0,1,0]
	v_pk_fma_f32 v[8:9], v[98:99], v[30:31], v[18:19] op_sel_hi:[1,0,1] neg_lo:[0,1,0] neg_hi:[0,1,0]
	v_pk_mul_f32 v[24:25], v[10:11], v[100:101] op_sel:[0,0] op_sel_hi:[0,1]
	v_pk_fma_f32 v[24:25], v[10:11], v[102:103], v[24:25] op_sel:[1,0,0] op_sel_hi:[1,1,1]
	v_pk_fma_f32 v[24:25], v[8:9], v[104:105], v[24:25] op_sel:[0,0,0] op_sel_hi:[0,1,1]
	v_pk_fma_f32 v[24:25], v[8:9], v[106:107], v[24:25] op_sel:[1,0,0] op_sel_hi:[1,1,1]
	v_pk_fma_f32 v[16:17], v[108:109], v[162:163], v[10:11] op_sel_hi:[1,0,1]
	v_pk_fma_f32 v[18:19], v[110:111], v[162:163], v[8:9] op_sel_hi:[1,0,1]
	v_add_f32_dpp v15, v24, v24 row_ror:8 row_mask:0xf bank_mask:0xf bound_ctrl:1
	v_add_f32_dpp v33, v25, v25 row_ror:8 row_mask:0xf bank_mask:0xf bound_ctrl:1
	ds_read_b128 v[76:79], v34 offset:24576
	v_add_f32_dpp v15, v15, v15 row_ror:4 row_mask:0xf bank_mask:0xf bound_ctrl:1
	ds_read_b128 v[80:83], v34 offset:24832
	ds_read_b128 v[84:87], v34 offset:25088
	v_add_f32_dpp v15, v15, v15 row_ror:2 row_mask:0xf bank_mask:0xf bound_ctrl:1
	ds_read_b128 v[88:91], v34 offset:25344
	ds_read_b128 v[144:147], v34 offset:33536
	ds_write2st64_b32 v37, v32, v33 offset0:40 offset1:42
	v_add_f32_dpp v30, v15, v15 row_ror:1 row_mask:0xf bank_mask:0xf bound_ctrl:1
	s_waitcnt lgkmcnt(5)
	v_pk_fma_f32 v[10:11], v[112:113], v[30:31], v[16:17] op_sel_hi:[1,0,1] neg_lo:[0,1,0] neg_hi:[0,1,0]
	v_pk_fma_f32 v[8:9], v[114:115], v[30:31], v[18:19] op_sel_hi:[1,0,1] neg_lo:[0,1,0] neg_hi:[0,1,0]
	v_pk_mul_f32 v[24:25], v[10:11], v[116:117] op_sel:[0,0] op_sel_hi:[0,1]
	v_pk_fma_f32 v[24:25], v[10:11], v[118:119], v[24:25] op_sel:[1,0,0] op_sel_hi:[1,1,1]
	v_pk_fma_f32 v[24:25], v[8:9], v[120:121], v[24:25] op_sel:[0,0,0] op_sel_hi:[0,1,1]
	v_pk_fma_f32 v[24:25], v[8:9], v[122:123], v[24:25] op_sel:[1,0,0] op_sel_hi:[1,1,1]
	v_pk_fma_f32 v[16:17], v[124:125], v[162:163], v[10:11] op_sel:[0,1,0] op_sel_hi:[1,1,1]
	v_pk_fma_f32 v[18:19], v[126:127], v[162:163], v[8:9] op_sel:[0,1,0] op_sel_hi:[1,1,1]
	v_add_f32_dpp v15, v24, v24 row_ror:8 row_mask:0xf bank_mask:0xf bound_ctrl:1
	v_add_f32_dpp v32, v25, v25 row_ror:8 row_mask:0xf bank_mask:0xf bound_ctrl:1
	ds_read_b128 v[92:95], v34 offset:25600
	v_add_f32_dpp v15, v15, v15 row_ror:4 row_mask:0xf bank_mask:0xf bound_ctrl:1
	ds_read_b128 v[96:99], v34 offset:25856
	ds_read_b128 v[100:103], v34 offset:26112
	v_add_f32_dpp v15, v15, v15 row_ror:2 row_mask:0xf bank_mask:0xf bound_ctrl:1
	ds_read_b128 v[104:107], v34 offset:26368
	s_nop 0
	v_add_f32_dpp v30, v15, v15 row_ror:1 row_mask:0xf bank_mask:0xf bound_ctrl:1
	v_pk_fma_f32 v[10:11], v[128:129], v[30:31], v[16:17] op_sel_hi:[1,0,1] neg_lo:[0,1,0] neg_hi:[0,1,0]
	v_pk_fma_f32 v[8:9], v[130:131], v[30:31], v[18:19] op_sel_hi:[1,0,1] neg_lo:[0,1,0] neg_hi:[0,1,0]
	v_pk_mul_f32 v[24:25], v[10:11], v[132:133] op_sel:[0,0] op_sel_hi:[0,1]
	v_pk_fma_f32 v[24:25], v[10:11], v[134:135], v[24:25] op_sel:[1,0,0] op_sel_hi:[1,1,1]
	v_pk_fma_f32 v[24:25], v[8:9], v[136:137], v[24:25] op_sel:[0,0,0] op_sel_hi:[0,1,1]
	v_pk_fma_f32 v[24:25], v[8:9], v[138:139], v[24:25] op_sel:[1,0,0] op_sel_hi:[1,1,1]
	s_nop 1
	v_add_f32_dpp v33, v25, v25 row_ror:8 row_mask:0xf bank_mask:0xf bound_ctrl:1
	ds_write2st64_b32 v37, v32, v33 offset0:44 offset1:46
	v_pk_mul_f32 v[10:11], v[10:11], v[140:141]
	v_pk_mul_f32 v[8:9], v[8:9], v[142:143]
	s_waitcnt lgkmcnt(6)
	v_pk_mul_f32 v[24:25], v[10:11], v[144:145]
	v_pk_fma_f32 v[24:25], v[8:9], v[146:147], v[24:25]
	v_add_f32_e32 v24, v24, v25
	v_pk_fma_f32 v[16:17], v[76:77], v[156:157], v[10:11] op_sel_hi:[1,0,1]
	v_pk_fma_f32 v[18:19], v[78:79], v[156:157], v[8:9] op_sel_hi:[1,0,1]
	v_add_f32_dpp v15, v24, v24 row_ror:8 row_mask:0xf bank_mask:0xf bound_ctrl:1
	ds_read_b128 v[108:111], v34 offset:26624
	ds_read_b128 v[112:115], v34 offset:26880
	v_add_f32_dpp v15, v15, v15 row_ror:4 row_mask:0xf bank_mask:0xf bound_ctrl:1
	ds_read_b128 v[116:119], v34 offset:27136
	ds_read_b128 v[120:123], v34 offset:27392
	v_add_f32_dpp v15, v15, v15 row_ror:2 row_mask:0xf bank_mask:0xf bound_ctrl:1
	s_nop 1
	v_add_f32_dpp v30, v15, v15 row_ror:1 row_mask:0xf bank_mask:0xf bound_ctrl:1
	s_waitcnt lgkmcnt(3)
	v_pk_fma_f32 v[10:11], v[80:81], v[30:31], v[16:17] op_sel_hi:[1,0,1] neg_lo:[0,1,0] neg_hi:[0,1,0]
	v_pk_fma_f32 v[8:9], v[82:83], v[30:31], v[18:19] op_sel_hi:[1,0,1] neg_lo:[0,1,0] neg_hi:[0,1,0]
	v_pk_mul_f32 v[24:25], v[10:11], v[84:85] op_sel:[0,0] op_sel_hi:[0,1]
	v_pk_fma_f32 v[24:25], v[10:11], v[86:87], v[24:25] op_sel:[1,0,0] op_sel_hi:[1,1,1]
	v_pk_fma_f32 v[24:25], v[8:9], v[88:89], v[24:25] op_sel:[0,0,0] op_sel_hi:[0,1,1]
	v_pk_fma_f32 v[24:25], v[8:9], v[90:91], v[24:25] op_sel:[1,0,0] op_sel_hi:[1,1,1]
	v_pk_fma_f32 v[16:17], v[92:93], v[156:157], v[10:11] op_sel:[0,1,0] op_sel_hi:[1,1,1]
	v_pk_fma_f32 v[18:19], v[94:95], v[156:157], v[8:9] op_sel:[0,1,0] op_sel_hi:[1,1,1]
	v_add_f32_dpp v15, v24, v24 row_ror:8 row_mask:0xf bank_mask:0xf bound_ctrl:1
	v_add_f32_dpp v32, v25, v25 row_ror:8 row_mask:0xf bank_mask:0xf bound_ctrl:1
	ds_read_b128 v[124:127], v34 offset:27648
	v_add_f32_dpp v15, v15, v15 row_ror:4 row_mask:0xf bank_mask:0xf bound_ctrl:1
	ds_read_b128 v[128:131], v34 offset:27904
	ds_read_b128 v[132:135], v34 offset:28160
	v_add_f32_dpp v15, v15, v15 row_ror:2 row_mask:0xf bank_mask:0xf bound_ctrl:1
	ds_read_b128 v[136:139], v34 offset:28416
	ds_read_b128 v[160:163], v35 offset:112
	v_add_f32_dpp v30, v15, v15 row_ror:1 row_mask:0xf bank_mask:0xf bound_ctrl:1
	v_pk_fma_f32 v[10:11], v[96:97], v[30:31], v[16:17] op_sel_hi:[1,0,1] neg_lo:[0,1,0] neg_hi:[0,1,0]
	v_pk_fma_f32 v[8:9], v[98:99], v[30:31], v[18:19] op_sel_hi:[1,0,1] neg_lo:[0,1,0] neg_hi:[0,1,0]
	v_pk_mul_f32 v[24:25], v[10:11], v[100:101] op_sel:[0,0] op_sel_hi:[0,1]
	v_pk_fma_f32 v[24:25], v[10:11], v[102:103], v[24:25] op_sel:[1,0,0] op_sel_hi:[1,1,1]
	v_pk_fma_f32 v[24:25], v[8:9], v[104:105], v[24:25] op_sel:[0,0,0] op_sel_hi:[0,1,1]
	v_pk_fma_f32 v[24:25], v[8:9], v[106:107], v[24:25] op_sel:[1,0,0] op_sel_hi:[1,1,1]
	v_pk_fma_f32 v[16:17], v[108:109], v[158:159], v[10:11] op_sel_hi:[1,0,1]
	v_pk_fma_f32 v[18:19], v[110:111], v[158:159], v[8:9] op_sel_hi:[1,0,1]
	v_add_f32_dpp v15, v24, v24 row_ror:8 row_mask:0xf bank_mask:0xf bound_ctrl:1
	v_add_f32_dpp v33, v25, v25 row_ror:8 row_mask:0xf bank_mask:0xf bound_ctrl:1
	ds_read_b128 v[76:79], v34 offset:28672
	v_add_f32_dpp v15, v15, v15 row_ror:4 row_mask:0xf bank_mask:0xf bound_ctrl:1
	ds_read_b128 v[80:83], v34 offset:28928
	ds_read_b128 v[84:87], v34 offset:29184
	v_add_f32_dpp v15, v15, v15 row_ror:2 row_mask:0xf bank_mask:0xf bound_ctrl:1
	ds_read_b128 v[88:91], v34 offset:29440
	ds_write2st64_b32 v37, v32, v33 offset0:48 offset1:50
	v_add_f32_dpp v30, v15, v15 row_ror:1 row_mask:0xf bank_mask:0xf bound_ctrl:1
	ds_read_b128 v[56:59], v52
	s_waitcnt lgkmcnt(5)
	v_pk_fma_f32 v[10:11], v[112:113], v[30:31], v[16:17] op_sel_hi:[1,0,1] neg_lo:[0,1,0] neg_hi:[0,1,0]
	v_pk_fma_f32 v[8:9], v[114:115], v[30:31], v[18:19] op_sel_hi:[1,0,1] neg_lo:[0,1,0] neg_hi:[0,1,0]
	v_pk_mul_f32 v[24:25], v[10:11], v[116:117] op_sel:[0,0] op_sel_hi:[0,1]
	v_pk_fma_f32 v[24:25], v[10:11], v[118:119], v[24:25] op_sel:[1,0,0] op_sel_hi:[1,1,1]
	v_pk_fma_f32 v[24:25], v[8:9], v[120:121], v[24:25] op_sel:[0,0,0] op_sel_hi:[0,1,1]
	v_pk_fma_f32 v[24:25], v[8:9], v[122:123], v[24:25] op_sel:[1,0,0] op_sel_hi:[1,1,1]
	v_pk_fma_f32 v[16:17], v[124:125], v[158:159], v[10:11] op_sel:[0,1,0] op_sel_hi:[1,1,1]
	v_pk_fma_f32 v[18:19], v[126:127], v[158:159], v[8:9] op_sel:[0,1,0] op_sel_hi:[1,1,1]
	v_add_f32_dpp v15, v24, v24 row_ror:8 row_mask:0xf bank_mask:0xf bound_ctrl:1
	v_add_f32_dpp v32, v25, v25 row_ror:8 row_mask:0xf bank_mask:0xf bound_ctrl:1
	ds_read_b128 v[92:95], v34 offset:29696
	v_add_f32_dpp v15, v15, v15 row_ror:4 row_mask:0xf bank_mask:0xf bound_ctrl:1
	ds_read_b128 v[96:99], v34 offset:29952
	ds_read_b128 v[100:103], v34 offset:30208
	v_add_f32_dpp v15, v15, v15 row_ror:2 row_mask:0xf bank_mask:0xf bound_ctrl:1
	ds_read_b128 v[104:107], v34 offset:30464
	s_nop 0
	v_add_f32_dpp v30, v15, v15 row_ror:1 row_mask:0xf bank_mask:0xf bound_ctrl:1
	s_waitcnt lgkmcnt(4)
	v_min_u32_e32 v56, v56, v57
	v_min3_u32 v56, v56, v58, v59
	v_pk_fma_f32 v[10:11], v[128:129], v[30:31], v[16:17] op_sel_hi:[1,0,1] neg_lo:[0,1,0] neg_hi:[0,1,0]
	v_pk_fma_f32 v[8:9], v[130:131], v[30:31], v[18:19] op_sel_hi:[1,0,1] neg_lo:[0,1,0] neg_hi:[0,1,0]
	v_pk_mul_f32 v[24:25], v[10:11], v[132:133] op_sel:[0,0] op_sel_hi:[0,1]
	v_pk_fma_f32 v[24:25], v[10:11], v[134:135], v[24:25] op_sel:[1,0,0] op_sel_hi:[1,1,1]
	v_pk_fma_f32 v[24:25], v[8:9], v[136:137], v[24:25] op_sel:[0,0,0] op_sel_hi:[0,1,1]
	v_pk_fma_f32 v[24:25], v[8:9], v[138:139], v[24:25] op_sel:[1,0,0] op_sel_hi:[1,1,1]
	v_pk_fma_f32 v[16:17], v[76:77], v[160:161], v[10:11] op_sel_hi:[1,0,1]
	v_pk_fma_f32 v[18:19], v[78:79], v[160:161], v[8:9] op_sel_hi:[1,0,1]
	v_add_f32_dpp v15, v24, v24 row_ror:8 row_mask:0xf bank_mask:0xf bound_ctrl:1
	v_add_f32_dpp v33, v25, v25 row_ror:8 row_mask:0xf bank_mask:0xf bound_ctrl:1
	ds_read_b128 v[108:111], v34 offset:30720
	v_add_f32_dpp v15, v15, v15 row_ror:4 row_mask:0xf bank_mask:0xf bound_ctrl:1
	ds_read_b128 v[112:115], v34 offset:30976
	ds_read_b128 v[116:119], v34 offset:31232
	v_add_f32_dpp v15, v15, v15 row_ror:2 row_mask:0xf bank_mask:0xf bound_ctrl:1
	ds_read_b128 v[120:123], v34 offset:31488
	ds_read_b128 v[140:143], v34 offset:34560
	ds_write2st64_b32 v37, v32, v33 offset0:52 offset1:54
	v_add_f32_dpp v30, v15, v15 row_ror:1 row_mask:0xf bank_mask:0xf bound_ctrl:1
	s_waitcnt lgkmcnt(5)
	v_pk_fma_f32 v[10:11], v[80:81], v[30:31], v[16:17] op_sel_hi:[1,0,1] neg_lo:[0,1,0] neg_hi:[0,1,0]
	v_pk_fma_f32 v[8:9], v[82:83], v[30:31], v[18:19] op_sel_hi:[1,0,1] neg_lo:[0,1,0] neg_hi:[0,1,0]
	v_pk_mul_f32 v[24:25], v[10:11], v[84:85] op_sel:[0,0] op_sel_hi:[0,1]
	v_pk_fma_f32 v[24:25], v[10:11], v[86:87], v[24:25] op_sel:[1,0,0] op_sel_hi:[1,1,1]
	v_pk_fma_f32 v[24:25], v[8:9], v[88:89], v[24:25] op_sel:[0,0,0] op_sel_hi:[0,1,1]
	v_pk_fma_f32 v[24:25], v[8:9], v[90:91], v[24:25] op_sel:[1,0,0] op_sel_hi:[1,1,1]
	v_pk_fma_f32 v[16:17], v[92:93], v[160:161], v[10:11] op_sel:[0,1,0] op_sel_hi:[1,1,1]
	v_pk_fma_f32 v[18:19], v[94:95], v[160:161], v[8:9] op_sel:[0,1,0] op_sel_hi:[1,1,1]
	v_add_f32_dpp v15, v24, v24 row_ror:8 row_mask:0xf bank_mask:0xf bound_ctrl:1
	v_add_f32_dpp v32, v25, v25 row_ror:8 row_mask:0xf bank_mask:0xf bound_ctrl:1
	ds_read_b128 v[124:127], v34 offset:31744
	v_add_f32_dpp v15, v15, v15 row_ror:4 row_mask:0xf bank_mask:0xf bound_ctrl:1
	ds_read_b128 v[128:131], v34 offset:32000
	ds_read_b128 v[132:135], v34 offset:32256
	v_add_f32_dpp v15, v15, v15 row_ror:2 row_mask:0xf bank_mask:0xf bound_ctrl:1
	ds_read_b128 v[136:139], v34 offset:32512
	s_nop 0
	v_add_f32_dpp v30, v15, v15 row_ror:1 row_mask:0xf bank_mask:0xf bound_ctrl:1
	v_readfirstlane_b32 s54, v56
	s_add_u32 s64, s6, 2
	s_cmp_lt_u32 s54, s64
	s_cbranch_scc1 .Lss_spin_0
.Lss_ok_0:
	v_pk_fma_f32 v[10:11], v[96:97], v[30:31], v[16:17] op_sel_hi:[1,0,1] neg_lo:[0,1,0] neg_hi:[0,1,0]
	v_pk_fma_f32 v[8:9], v[98:99], v[30:31], v[18:19] op_sel_hi:[1,0,1] neg_lo:[0,1,0] neg_hi:[0,1,0]
	v_pk_mul_f32 v[24:25], v[10:11], v[100:101] op_sel:[0,0] op_sel_hi:[0,1]
	v_pk_fma_f32 v[24:25], v[10:11], v[102:103], v[24:25] op_sel:[1,0,0] op_sel_hi:[1,1,1]
	v_pk_fma_f32 v[24:25], v[8:9], v[104:105], v[24:25] op_sel:[0,0,0] op_sel_hi:[0,1,1]
	v_pk_fma_f32 v[24:25], v[8:9], v[106:107], v[24:25] op_sel:[1,0,0] op_sel_hi:[1,1,1]
	v_pk_fma_f32 v[16:17], v[108:109], v[162:163], v[10:11] op_sel_hi:[1,0,1]
	v_pk_fma_f32 v[18:19], v[110:111], v[162:163], v[8:9] op_sel_hi:[1,0,1]
	v_add_f32_dpp v15, v24, v24 row_ror:8 row_mask:0xf bank_mask:0xf bound_ctrl:1
	v_add_f32_dpp v33, v25, v25 row_ror:8 row_mask:0xf bank_mask:0xf bound_ctrl:1
	ds_read_b128 v[76:79], v48 offset:0
	v_add_f32_dpp v15, v15, v15 row_ror:4 row_mask:0xf bank_mask:0xf bound_ctrl:1
	ds_read_b128 v[80:83], v48 offset:256
	ds_read_b128 v[84:87], v48 offset:512
	v_add_f32_dpp v15, v15, v15 row_ror:2 row_mask:0xf bank_mask:0xf bound_ctrl:1
	ds_read_b128 v[88:91], v48 offset:768
	ds_read_b128 v[144:147], v48 offset:32768
	ds_write2st64_b32 v37, v32, v33 offset0:56 offset1:58
	v_add_f32_dpp v30, v15, v15 row_ror:1 row_mask:0xf bank_mask:0xf bound_ctrl:1
	ds_read_b128 v[156:159], v49 offset:0
	s_waitcnt lgkmcnt(6)
	v_pk_fma_f32 v[10:11], v[112:113], v[30:31], v[16:17] op_sel_hi:[1,0,1] neg_lo:[0,1,0] neg_hi:[0,1,0]
	v_pk_fma_f32 v[8:9], v[114:115], v[30:31], v[18:19] op_sel_hi:[1,0,1] neg_lo:[0,1,0] neg_hi:[0,1,0]
	v_pk_mul_f32 v[24:25], v[10:11], v[116:117] op_sel:[0,0] op_sel_hi:[0,1]
	v_pk_fma_f32 v[24:25], v[10:11], v[118:119], v[24:25] op_sel:[1,0,0] op_sel_hi:[1,1,1]
	v_pk_fma_f32 v[24:25], v[8:9], v[120:121], v[24:25] op_sel:[0,0,0] op_sel_hi:[0,1,1]
	v_pk_fma_f32 v[24:25], v[8:9], v[122:123], v[24:25] op_sel:[1,0,0] op_sel_hi:[1,1,1]
	v_pk_fma_f32 v[16:17], v[124:125], v[162:163], v[10:11] op_sel:[0,1,0] op_sel_hi:[1,1,1]
	v_pk_fma_f32 v[18:19], v[126:127], v[162:163], v[8:9] op_sel:[0,1,0] op_sel_hi:[1,1,1]
	v_add_f32_dpp v15, v24, v24 row_ror:8 row_mask:0xf bank_mask:0xf bound_ctrl:1
	v_add_f32_dpp v32, v25, v25 row_ror:8 row_mask:0xf bank_mask:0xf bound_ctrl:1
	ds_read_b128 v[92:95], v48 offset:1024
	v_add_f32_dpp v15, v15, v15 row_ror:4 row_mask:0xf bank_mask:0xf bound_ctrl:1
	ds_read_b128 v[96:99], v48 offset:1280
	ds_read_b128 v[100:103], v48 offset:1536
	v_add_f32_dpp v15, v15, v15 row_ror:2 row_mask:0xf bank_mask:0xf bound_ctrl:1
	ds_read_b128 v[104:107], v48 offset:1792
	s_nop 0
	v_add_f32_dpp v30, v15, v15 row_ror:1 row_mask:0xf bank_mask:0xf bound_ctrl:1
	v_pk_fma_f32 v[10:11], v[128:129], v[30:31], v[16:17] op_sel_hi:[1,0,1] neg_lo:[0,1,0] neg_hi:[0,1,0]
	v_pk_fma_f32 v[8:9], v[130:131], v[30:31], v[18:19] op_sel_hi:[1,0,1] neg_lo:[0,1,0] neg_hi:[0,1,0]
	v_pk_mul_f32 v[24:25], v[10:11], v[132:133] op_sel:[0,0] op_sel_hi:[0,1]
	v_pk_fma_f32 v[24:25], v[10:11], v[134:135], v[24:25] op_sel:[1,0,0] op_sel_hi:[1,1,1]
	v_pk_fma_f32 v[24:25], v[8:9], v[136:137], v[24:25] op_sel:[0,0,0] op_sel_hi:[0,1,1]
	v_pk_fma_f32 v[24:25], v[8:9], v[138:139], v[24:25] op_sel:[1,0,0] op_sel_hi:[1,1,1]
	s_nop 1
	v_add_f32_dpp v33, v25, v25 row_ror:8 row_mask:0xf bank_mask:0xf bound_ctrl:1
	ds_write2st64_b32 v37, v32, v33 offset0:60 offset1:62
	v_pk_mul_f32 v[10:11], v[10:11], v[140:141]
	v_pk_mul_f32 v[8:9], v[8:9], v[142:143]
	s_waitcnt lgkmcnt(7)
	v_pk_mul_f32 v[24:25], v[10:11], v[144:145]
	v_pk_fma_f32 v[24:25], v[8:9], v[146:147], v[24:25]
	v_add_f32_e32 v24, v24, v25
	s_waitcnt lgkmcnt(5)
	v_pk_fma_f32 v[16:17], v[76:77], v[156:157], v[10:11] op_sel_hi:[1,0,1]
	v_pk_fma_f32 v[18:19], v[78:79], v[156:157], v[8:9] op_sel_hi:[1,0,1]
	v_add_f32_dpp v15, v24, v24 row_ror:8 row_mask:0xf bank_mask:0xf bound_ctrl:1
	v_add_u32_e32 v51, 1, v51
	s_add_u32 s6, s6, 1
	v_add_f32_dpp v15, v15, v15 row_ror:4 row_mask:0xf bank_mask:0xf bound_ctrl:1
	ds_write_b32 v53, v51
	ds_read_b128 v[108:111], v48 offset:2048
	v_add_f32_dpp v15, v15, v15 row_ror:2 row_mask:0xf bank_mask:0xf bound_ctrl:1
	ds_read_b128 v[112:115], v48 offset:2304
	ds_read_b128 v[116:119], v48 offset:2560
	v_add_f32_dpp v30, v15, v15 row_ror:1 row_mask:0xf bank_mask:0xf bound_ctrl:1
	ds_read_b128 v[120:123], v48 offset:2816
	s_waitcnt lgkmcnt(3)
	v_pk_fma_f32 v[10:11], v[80:81], v[30:31], v[16:17] op_sel_hi:[1,0,1] neg_lo:[0,1,0] neg_hi:[0,1,0]
	v_pk_fma_f32 v[8:9], v[82:83], v[30:31], v[18:19] op_sel_hi:[1,0,1] neg_lo:[0,1,0] neg_hi:[0,1,0]
	v_pk_mul_f32 v[24:25], v[10:11], v[84:85] op_sel:[0,0] op_sel_hi:[0,1]
	v_pk_fma_f32 v[24:25], v[10:11], v[86:87], v[24:25] op_sel:[1,0,0] op_sel_hi:[1,1,1]
	v_pk_fma_f32 v[24:25], v[8:9], v[88:89], v[24:25] op_sel:[0,0,0] op_sel_hi:[0,1,1]
	v_pk_fma_f32 v[24:25], v[8:9], v[90:91], v[24:25] op_sel:[1,0,0] op_sel_hi:[1,1,1]
	v_pk_fma_f32 v[16:17], v[92:93], v[156:157], v[10:11] op_sel:[0,1,0] op_sel_hi:[1,1,1]
	v_pk_fma_f32 v[18:19], v[94:95], v[156:157], v[8:9] op_sel:[0,1,0] op_sel_hi:[1,1,1]
	v_add_f32_dpp v15, v24, v24 row_ror:8 row_mask:0xf bank_mask:0xf bound_ctrl:1
	v_add_f32_dpp v32, v25, v25 row_ror:8 row_mask:0xf bank_mask:0xf bound_ctrl:1
	ds_read_b128 v[124:127], v48 offset:3072
	v_add_f32_dpp v15, v15, v15 row_ror:4 row_mask:0xf bank_mask:0xf bound_ctrl:1
	ds_read_b128 v[128:131], v48 offset:3328
	ds_read_b128 v[132:135], v48 offset:3584
	v_add_f32_dpp v15, v15, v15 row_ror:2 row_mask:0xf bank_mask:0xf bound_ctrl:1
	ds_read_b128 v[136:139], v48 offset:3840
	ds_read_b128 v[160:163], v49 offset:16
	v_add_f32_dpp v30, v15, v15 row_ror:1 row_mask:0xf bank_mask:0xf bound_ctrl:1
	v_pk_fma_f32 v[10:11], v[96:97], v[30:31], v[16:17] op_sel_hi:[1,0,1] neg_lo:[0,1,0] neg_hi:[0,1,0]
	v_pk_fma_f32 v[8:9], v[98:99], v[30:31], v[18:19] op_sel_hi:[1,0,1] neg_lo:[0,1,0] neg_hi:[0,1,0]
	v_pk_mul_f32 v[24:25], v[10:11], v[100:101] op_sel:[0,0] op_sel_hi:[0,1]
	v_pk_fma_f32 v[24:25], v[10:11], v[102:103], v[24:25] op_sel:[1,0,0] op_sel_hi:[1,1,1]
	v_pk_fma_f32 v[24:25], v[8:9], v[104:105], v[24:25] op_sel:[0,0,0] op_sel_hi:[0,1,1]
	v_pk_fma_f32 v[24:25], v[8:9], v[106:107], v[24:25] op_sel:[1,0,0] op_sel_hi:[1,1,1]
	v_pk_fma_f32 v[16:17], v[108:109], v[158:159], v[10:11] op_sel_hi:[1,0,1]
	v_pk_fma_f32 v[18:19], v[110:111], v[158:159], v[8:9] op_sel_hi:[1,0,1]
	v_add_f32_dpp v15, v24, v24 row_ror:8 row_mask:0xf bank_mask:0xf bound_ctrl:1
	v_add_f32_dpp v33, v25, v25 row_ror:8 row_mask:0xf bank_mask:0xf bound_ctrl:1
	ds_read_b128 v[76:79], v48 offset:4096
	v_add_f32_dpp v15, v15, v15 row_ror:4 row_mask:0xf bank_mask:0xf bound_ctrl:1
	ds_read_b128 v[80:83], v48 offset:4352
	ds_read_b128 v[84:87], v48 offset:4608
	v_add_f32_dpp v15, v15, v15 row_ror:2 row_mask:0xf bank_mask:0xf bound_ctrl:1
	ds_read_b128 v[88:91], v48 offset:4864
	ds_write2st64_b32 v50, v32, v33 offset0:0 offset1:2
	v_add_f32_dpp v30, v15, v15 row_ror:1 row_mask:0xf bank_mask:0xf bound_ctrl:1
	s_waitcnt lgkmcnt(4)
	v_pk_fma_f32 v[10:11], v[112:113], v[30:31], v[16:17] op_sel_hi:[1,0,1] neg_lo:[0,1,0] neg_hi:[0,1,0]
	v_pk_fma_f32 v[8:9], v[114:115], v[30:31], v[18:19] op_sel_hi:[1,0,1] neg_lo:[0,1,0] neg_hi:[0,1,0]
	v_pk_mul_f32 v[24:25], v[10:11], v[116:117] op_sel:[0,0] op_sel_hi:[0,1]
	v_pk_fma_f32 v[24:25], v[10:11], v[118:119], v[24:25] op_sel:[1,0,0] op_sel_hi:[1,1,1]
	v_pk_fma_f32 v[24:25], v[8:9], v[120:121], v[24:25] op_sel:[0,0,0] op_sel_hi:[0,1,1]
	v_pk_fma_f32 v[24:25], v[8:9], v[122:123], v[24:25] op_sel:[1,0,0] op_sel_hi:[1,1,1]
	v_pk_fma_f32 v[16:17], v[124:125], v[158:159], v[10:11] op_sel:[0,1,0] op_sel_hi:[1,1,1]
	v_pk_fma_f32 v[18:19], v[126:127], v[158:159], v[8:9] op_sel:[0,1,0] op_sel_hi:[1,1,1]
	v_add_f32_dpp v15, v24, v24 row_ror:8 row_mask:0xf bank_mask:0xf bound_ctrl:1
	v_add_f32_dpp v32, v25, v25 row_ror:8 row_mask:0xf bank_mask:0xf bound_ctrl:1
	ds_read_b128 v[92:95], v48 offset:5120
	v_add_f32_dpp v15, v15, v15 row_ror:4 row_mask:0xf bank_mask:0xf bound_ctrl:1
	ds_read_b128 v[96:99], v48 offset:5376
	ds_read_b128 v[100:103], v48 offset:5632
	v_add_f32_dpp v15, v15, v15 row_ror:2 row_mask:0xf bank_mask:0xf bound_ctrl:1
	ds_read_b128 v[104:107], v48 offset:5888
	s_nop 0
	v_add_f32_dpp v30, v15, v15 row_ror:1 row_mask:0xf bank_mask:0xf bound_ctrl:1
	v_pk_fma_f32 v[10:11], v[128:129], v[30:31], v[16:17] op_sel_hi:[1,0,1] neg_lo:[0,1,0] neg_hi:[0,1,0]
	v_pk_fma_f32 v[8:9], v[130:131], v[30:31], v[18:19] op_sel_hi:[1,0,1] neg_lo:[0,1,0] neg_hi:[0,1,0]
	v_pk_mul_f32 v[24:25], v[10:11], v[132:133] op_sel:[0,0] op_sel_hi:[0,1]
	v_pk_fma_f32 v[24:25], v[10:11], v[134:135], v[24:25] op_sel:[1,0,0] op_sel_hi:[1,1,1]
	v_pk_fma_f32 v[24:25], v[8:9], v[136:137], v[24:25] op_sel:[0,0,0] op_sel_hi:[0,1,1]
	v_pk_fma_f32 v[24:25], v[8:9], v[138:139], v[24:25] op_sel:[1,0,0] op_sel_hi:[1,1,1]
	v_pk_fma_f32 v[16:17], v[76:77], v[160:161], v[10:11] op_sel_hi:[1,0,1]
	v_pk_fma_f32 v[18:19], v[78:79], v[160:161], v[8:9] op_sel_hi:[1,0,1]
	v_add_f32_dpp v15, v24, v24 row_ror:8 row_mask:0xf bank_mask:0xf bound_ctrl:1
	v_add_f32_dpp v33, v25, v25 row_ror:8 row_mask:0xf bank_mask:0xf bound_ctrl:1
	ds_read_b128 v[108:111], v48 offset:6144
	v_add_f32_dpp v15, v15, v15 row_ror:4 row_mask:0xf bank_mask:0xf bound_ctrl:1
	ds_read_b128 v[112:115], v48 offset:6400
	ds_read_b128 v[116:119], v48 offset:6656
	v_add_f32_dpp v15, v15, v15 row_ror:2 row_mask:0xf bank_mask:0xf bound_ctrl:1
	ds_read_b128 v[120:123], v48 offset:6912
	ds_read_b128 v[140:143], v48 offset:33792
	ds_write2st64_b32 v50, v32, v33 offset0:4 offset1:6
	v_add_f32_dpp v30, v15, v15 row_ror:1 row_mask:0xf bank_mask:0xf bound_ctrl:1
	s_waitcnt lgkmcnt(5)
	v_pk_fma_f32 v[10:11], v[80:81], v[30:31], v[16:17] op_sel_hi:[1,0,1] neg_lo:[0,1,0] neg_hi:[0,1,0]
	v_pk_fma_f32 v[8:9], v[82:83], v[30:31], v[18:19] op_sel_hi:[1,0,1] neg_lo:[0,1,0] neg_hi:[0,1,0]
	v_pk_mul_f32 v[24:25], v[10:11], v[84:85] op_sel:[0,0] op_sel_hi:[0,1]
	v_pk_fma_f32 v[24:25], v[10:11], v[86:87], v[24:25] op_sel:[1,0,0] op_sel_hi:[1,1,1]
	v_pk_fma_f32 v[24:25], v[8:9], v[88:89], v[24:25] op_sel:[0,0,0] op_sel_hi:[0,1,1]
	v_pk_fma_f32 v[24:25], v[8:9], v[90:91], v[24:25] op_sel:[1,0,0] op_sel_hi:[1,1,1]
	v_pk_fma_f32 v[16:17], v[92:93], v[160:161], v[10:11] op_sel:[0,1,0] op_sel_hi:[1,1,1]
	v_pk_fma_f32 v[18:19], v[94:95], v[160:161], v[8:9] op_sel:[0,1,0] op_sel_hi:[1,1,1]
	v_add_f32_dpp v15, v24, v24 row_ror:8 row_mask:0xf bank_mask:0xf bound_ctrl:1
	v_add_f32_dpp v32, v25, v25 row_ror:8 row_mask:0xf bank_mask:0xf bound_ctrl:1
	ds_read_b128 v[124:127], v48 offset:7168
	v_add_f32_dpp v15, v15, v15 row_ror:4 row_mask:0xf bank_mask:0xf bound_ctrl:1
	ds_read_b128 v[128:131], v48 offset:7424
	ds_read_b128 v[132:135], v48 offset:7680
	v_add_f32_dpp v15, v15, v15 row_ror:2 row_mask:0xf bank_mask:0xf bound_ctrl:1
	ds_read_b128 v[136:139], v48 offset:7936
	ds_read_b128 v[156:159], v49 offset:32
	v_add_f32_dpp v30, v15, v15 row_ror:1 row_mask:0xf bank_mask:0xf bound_ctrl:1
	v_pk_fma_f32 v[10:11], v[96:97], v[30:31], v[16:17] op_sel_hi:[1,0,1] neg_lo:[0,1,0] neg_hi:[0,1,0]
	v_pk_fma_f32 v[8:9], v[98:99], v[30:31], v[18:19] op_sel_hi:[1,0,1] neg_lo:[0,1,0] neg_hi:[0,1,0]
	v_pk_mul_f32 v[24:25], v[10:11], v[100:101] op_sel:[0,0] op_sel_hi:[0,1]
	v_pk_fma_f32 v[24:25], v[10:11], v[102:103], v[24:25] op_sel:[1,0,0] op_sel_hi:[1,1,1]
	v_pk_fma_f32 v[24:25], v[8:9], v[104:105], v[24:25] op_sel:[0,0,0] op_sel_hi:[0,1,1]
	v_pk_fma_f32 v[24:25], v[8:9], v[106:107], v[24:25] op_sel:[1,0,0] op_sel_hi:[1,1,1]
	v_pk_fma_f32 v[16:17], v[108:109], v[162:163], v[10:11] op_sel_hi:[1,0,1]
	v_pk_fma_f32 v[18:19], v[110:111], v[162:163], v[8:9] op_sel_hi:[1,0,1]
	v_add_f32_dpp v15, v24, v24 row_ror:8 row_mask:0xf bank_mask:0xf bound_ctrl:1
	v_add_f32_dpp v33, v25, v25 row_ror:8 row_mask:0xf bank_mask:0xf bound_ctrl:1
	ds_read_b128 v[76:79], v48 offset:8192
	v_add_f32_dpp v15, v15, v15 row_ror:4 row_mask:0xf bank_mask:0xf bound_ctrl:1
	ds_read_b128 v[80:83], v48 offset:8448
	ds_read_b128 v[84:87], v48 offset:8704
	v_add_f32_dpp v15, v15, v15 row_ror:2 row_mask:0xf bank_mask:0xf bound_ctrl:1
	ds_read_b128 v[88:91], v48 offset:8960
	ds_read_b128 v[144:147], v48 offset:33024
	ds_write2st64_b32 v50, v32, v33 offset0:8 offset1:10
	v_add_f32_dpp v30, v15, v15 row_ror:1 row_mask:0xf bank_mask:0xf bound_ctrl:1
	s_waitcnt lgkmcnt(5)
	v_pk_fma_f32 v[10:11], v[112:113], v[30:31], v[16:17] op_sel_hi:[1,0,1] neg_lo:[0,1,0] neg_hi:[0,1,0]
	v_pk_fma_f32 v[8:9], v[114:115], v[30:31], v[18:19] op_sel_hi:[1,0,1] neg_lo:[0,1,0] neg_hi:[0,1,0]
	v_pk_mul_f32 v[24:25], v[10:11], v[116:117] op_sel:[0,0] op_sel_hi:[0,1]
	v_pk_fma_f32 v[24:25], v[10:11], v[118:119], v[24:25] op_sel:[1,0,0] op_sel_hi:[1,1,1]
	v_pk_fma_f32 v[24:25], v[8:9], v[120:121], v[24:25] op_sel:[0,0,0] op_sel_hi:[0,1,1]
	v_pk_fma_f32 v[24:25], v[8:9], v[122:123], v[24:25] op_sel:[1,0,0] op_sel_hi:[1,1,1]
	v_pk_fma_f32 v[16:17], v[124:125], v[162:163], v[10:11] op_sel:[0,1,0] op_sel_hi:[1,1,1]
	v_pk_fma_f32 v[18:19], v[126:127], v[162:163], v[8:9] op_sel:[0,1,0] op_sel_hi:[1,1,1]
	v_add_f32_dpp v15, v24, v24 row_ror:8 row_mask:0xf bank_mask:0xf bound_ctrl:1
	v_add_f32_dpp v32, v25, v25 row_ror:8 row_mask:0xf bank_mask:0xf bound_ctrl:1
	ds_read_b128 v[92:95], v48 offset:9216
	v_add_f32_dpp v15, v15, v15 row_ror:4 row_mask:0xf bank_mask:0xf bound_ctrl:1
	ds_read_b128 v[96:99], v48 offset:9472
	ds_read_b128 v[100:103], v48 offset:9728
	v_add_f32_dpp v15, v15, v15 row_ror:2 row_mask:0xf bank_mask:0xf bound_ctrl:1
	ds_read_b128 v[104:107], v48 offset:9984
	s_nop 0
	v_add_f32_dpp v30, v15, v15 row_ror:1 row_mask:0xf bank_mask:0xf bound_ctrl:1
	v_pk_fma_f32 v[10:11], v[128:129], v[30:31], v[16:17] op_sel_hi:[1,0,1] neg_lo:[0,1,0] neg_hi:[0,1,0]
	v_pk_fma_f32 v[8:9], v[130:131], v[30:31], v[18:19] op_sel_hi:[1,0,1] neg_lo:[0,1,0] neg_hi:[0,1,0]
	v_pk_mul_f32 v[24:25], v[10:11], v[132:133] op_sel:[0,0] op_sel_hi:[0,1]
	v_pk_fma_f32 v[24:25], v[10:11], v[134:135], v[24:25] op_sel:[1,0,0] op_sel_hi:[1,1,1]
	v_pk_fma_f32 v[24:25], v[8:9], v[136:137], v[24:25] op_sel:[0,0,0] op_sel_hi:[0,1,1]
	v_pk_fma_f32 v[24:25], v[8:9], v[138:139], v[24:25] op_sel:[1,0,0] op_sel_hi:[1,1,1]
	s_nop 1
	v_add_f32_dpp v33, v25, v25 row_ror:8 row_mask:0xf bank_mask:0xf bound_ctrl:1
	ds_write2st64_b32 v50, v32, v33 offset0:12 offset1:14
	v_pk_mul_f32 v[10:11], v[10:11], v[140:141]
	v_pk_mul_f32 v[8:9], v[8:9], v[142:143]
	s_waitcnt lgkmcnt(6)
	v_pk_mul_f32 v[24:25], v[10:11], v[144:145]
	v_pk_fma_f32 v[24:25], v[8:9], v[146:147], v[24:25]
	v_add_f32_e32 v24, v24, v25
	v_pk_fma_f32 v[16:17], v[76:77], v[156:157], v[10:11] op_sel_hi:[1,0,1]
	v_pk_fma_f32 v[18:19], v[78:79], v[156:157], v[8:9] op_sel_hi:[1,0,1]
	v_add_f32_dpp v15, v24, v24 row_ror:8 row_mask:0xf bank_mask:0xf bound_ctrl:1
	ds_read_b128 v[108:111], v48 offset:10240
	ds_read_b128 v[112:115], v48 offset:10496
	v_add_f32_dpp v15, v15, v15 row_ror:4 row_mask:0xf bank_mask:0xf bound_ctrl:1
	ds_read_b128 v[116:119], v48 offset:10752
	ds_read_b128 v[120:123], v48 offset:11008
	v_add_f32_dpp v15, v15, v15 row_ror:2 row_mask:0xf bank_mask:0xf bound_ctrl:1
	s_nop 1
	v_add_f32_dpp v30, v15, v15 row_ror:1 row_mask:0xf bank_mask:0xf bound_ctrl:1
	s_waitcnt lgkmcnt(3)
	v_pk_fma_f32 v[10:11], v[80:81], v[30:31], v[16:17] op_sel_hi:[1,0,1] neg_lo:[0,1,0] neg_hi:[0,1,0]
	v_pk_fma_f32 v[8:9], v[82:83], v[30:31], v[18:19] op_sel_hi:[1,0,1] neg_lo:[0,1,0] neg_hi:[0,1,0]
	v_pk_mul_f32 v[24:25], v[10:11], v[84:85] op_sel:[0,0] op_sel_hi:[0,1]
	v_pk_fma_f32 v[24:25], v[10:11], v[86:87], v[24:25] op_sel:[1,0,0] op_sel_hi:[1,1,1]
	v_pk_fma_f32 v[24:25], v[8:9], v[88:89], v[24:25] op_sel:[0,0,0] op_sel_hi:[0,1,1]
	v_pk_fma_f32 v[24:25], v[8:9], v[90:91], v[24:25] op_sel:[1,0,0] op_sel_hi:[1,1,1]
	v_pk_fma_f32 v[16:17], v[92:93], v[156:157], v[10:11] op_sel:[0,1,0] op_sel_hi:[1,1,1]
	v_pk_fma_f32 v[18:19], v[94:95], v[156:157], v[8:9] op_sel:[0,1,0] op_sel_hi:[1,1,1]
	v_add_f32_dpp v15, v24, v24 row_ror:8 row_mask:0xf bank_mask:0xf bound_ctrl:1
	v_add_f32_dpp v32, v25, v25 row_ror:8 row_mask:0xf bank_mask:0xf bound_ctrl:1
	ds_read_b128 v[124:127], v48 offset:11264
	v_add_f32_dpp v15, v15, v15 row_ror:4 row_mask:0xf bank_mask:0xf bound_ctrl:1
	ds_read_b128 v[128:131], v48 offset:11520
	ds_read_b128 v[132:135], v48 offset:11776
	v_add_f32_dpp v15, v15, v15 row_ror:2 row_mask:0xf bank_mask:0xf bound_ctrl:1
	ds_read_b128 v[136:139], v48 offset:12032
	ds_read_b128 v[160:163], v49 offset:48
	v_add_f32_dpp v30, v15, v15 row_ror:1 row_mask:0xf bank_mask:0xf bound_ctrl:1
	v_pk_fma_f32 v[10:11], v[96:97], v[30:31], v[16:17] op_sel_hi:[1,0,1] neg_lo:[0,1,0] neg_hi:[0,1,0]
	v_pk_fma_f32 v[8:9], v[98:99], v[30:31], v[18:19] op_sel_hi:[1,0,1] neg_lo:[0,1,0] neg_hi:[0,1,0]
	v_pk_mul_f32 v[24:25], v[10:11], v[100:101] op_sel:[0,0] op_sel_hi:[0,1]
	v_pk_fma_f32 v[24:25], v[10:11], v[102:103], v[24:25] op_sel:[1,0,0] op_sel_hi:[1,1,1]
	v_pk_fma_f32 v[24:25], v[8:9], v[104:105], v[24:25] op_sel:[0,0,0] op_sel_hi:[0,1,1]
	v_pk_fma_f32 v[24:25], v[8:9], v[106:107], v[24:25] op_sel:[1,0,0] op_sel_hi:[1,1,1]
	v_pk_fma_f32 v[16:17], v[108:109], v[158:159], v[10:11] op_sel_hi:[1,0,1]
	v_pk_fma_f32 v[18:19], v[110:111], v[158:159], v[8:9] op_sel_hi:[1,0,1]
	v_add_f32_dpp v15, v24, v24 row_ror:8 row_mask:0xf bank_mask:0xf bound_ctrl:1
	v_add_f32_dpp v33, v25, v25 row_ror:8 row_mask:0xf bank_mask:0xf bound_ctrl:1
	ds_read_b128 v[76:79], v48 offset:12288
	v_add_f32_dpp v15, v15, v15 row_ror:4 row_mask:0xf bank_mask:0xf bound_ctrl:1
	ds_read_b128 v[80:83], v48 offset:12544
	ds_read_b128 v[84:87], v48 offset:12800
	v_add_f32_dpp v15, v15, v15 row_ror:2 row_mask:0xf bank_mask:0xf bound_ctrl:1
	ds_read_b128 v[88:91], v48 offset:13056
	ds_write2st64_b32 v50, v32, v33 offset0:16 offset1:18
	v_add_f32_dpp v30, v15, v15 row_ror:1 row_mask:0xf bank_mask:0xf bound_ctrl:1
	s_waitcnt lgkmcnt(4)
	v_pk_fma_f32 v[10:11], v[112:113], v[30:31], v[16:17] op_sel_hi:[1,0,1] neg_lo:[0,1,0] neg_hi:[0,1,0]
	v_pk_fma_f32 v[8:9], v[114:115], v[30:31], v[18:19] op_sel_hi:[1,0,1] neg_lo:[0,1,0] neg_hi:[0,1,0]
	v_pk_mul_f32 v[24:25], v[10:11], v[116:117] op_sel:[0,0] op_sel_hi:[0,1]
	v_pk_fma_f32 v[24:25], v[10:11], v[118:119], v[24:25] op_sel:[1,0,0] op_sel_hi:[1,1,1]
	v_pk_fma_f32 v[24:25], v[8:9], v[120:121], v[24:25] op_sel:[0,0,0] op_sel_hi:[0,1,1]
	v_pk_fma_f32 v[24:25], v[8:9], v[122:123], v[24:25] op_sel:[1,0,0] op_sel_hi:[1,1,1]
	v_pk_fma_f32 v[16:17], v[124:125], v[158:159], v[10:11] op_sel:[0,1,0] op_sel_hi:[1,1,1]
	v_pk_fma_f32 v[18:19], v[126:127], v[158:159], v[8:9] op_sel:[0,1,0] op_sel_hi:[1,1,1]
	v_add_f32_dpp v15, v24, v24 row_ror:8 row_mask:0xf bank_mask:0xf bound_ctrl:1
	v_add_f32_dpp v32, v25, v25 row_ror:8 row_mask:0xf bank_mask:0xf bound_ctrl:1
	ds_read_b128 v[92:95], v48 offset:13312
	v_add_f32_dpp v15, v15, v15 row_ror:4 row_mask:0xf bank_mask:0xf bound_ctrl:1
	ds_read_b128 v[96:99], v48 offset:13568
	ds_read_b128 v[100:103], v48 offset:13824
	v_add_f32_dpp v15, v15, v15 row_ror:2 row_mask:0xf bank_mask:0xf bound_ctrl:1
	ds_read_b128 v[104:107], v48 offset:14080
	s_nop 0
	v_add_f32_dpp v30, v15, v15 row_ror:1 row_mask:0xf bank_mask:0xf bound_ctrl:1
	v_pk_fma_f32 v[10:11], v[128:129], v[30:31], v[16:17] op_sel_hi:[1,0,1] neg_lo:[0,1,0] neg_hi:[0,1,0]
	v_pk_fma_f32 v[8:9], v[130:131], v[30:31], v[18:19] op_sel_hi:[1,0,1] neg_lo:[0,1,0] neg_hi:[0,1,0]
	v_pk_mul_f32 v[24:25], v[10:11], v[132:133] op_sel:[0,0] op_sel_hi:[0,1]
	v_pk_fma_f32 v[24:25], v[10:11], v[134:135], v[24:25] op_sel:[1,0,0] op_sel_hi:[1,1,1]
	v_pk_fma_f32 v[24:25], v[8:9], v[136:137], v[24:25] op_sel:[0,0,0] op_sel_hi:[0,1,1]
	v_pk_fma_f32 v[24:25], v[8:9], v[138:139], v[24:25] op_sel:[1,0,0] op_sel_hi:[1,1,1]
	v_pk_fma_f32 v[16:17], v[76:77], v[160:161], v[10:11] op_sel_hi:[1,0,1]
	v_pk_fma_f32 v[18:19], v[78:79], v[160:161], v[8:9] op_sel_hi:[1,0,1]
	v_add_f32_dpp v15, v24, v24 row_ror:8 row_mask:0xf bank_mask:0xf bound_ctrl:1
	v_add_f32_dpp v33, v25, v25 row_ror:8 row_mask:0xf bank_mask:0xf bound_ctrl:1
	ds_read_b128 v[108:111], v48 offset:14336
	v_add_f32_dpp v15, v15, v15 row_ror:4 row_mask:0xf bank_mask:0xf bound_ctrl:1
	ds_read_b128 v[112:115], v48 offset:14592
	ds_read_b128 v[116:119], v48 offset:14848
	v_add_f32_dpp v15, v15, v15 row_ror:2 row_mask:0xf bank_mask:0xf bound_ctrl:1
	ds_read_b128 v[120:123], v48 offset:15104
	ds_read_b128 v[140:143], v48 offset:34048
	ds_write2st64_b32 v50, v32, v33 offset0:20 offset1:22
	v_add_f32_dpp v30, v15, v15 row_ror:1 row_mask:0xf bank_mask:0xf bound_ctrl:1
	s_waitcnt lgkmcnt(5)
	v_pk_fma_f32 v[10:11], v[80:81], v[30:31], v[16:17] op_sel_hi:[1,0,1] neg_lo:[0,1,0] neg_hi:[0,1,0]
	v_pk_fma_f32 v[8:9], v[82:83], v[30:31], v[18:19] op_sel_hi:[1,0,1] neg_lo:[0,1,0] neg_hi:[0,1,0]
	v_pk_mul_f32 v[24:25], v[10:11], v[84:85] op_sel:[0,0] op_sel_hi:[0,1]
	v_pk_fma_f32 v[24:25], v[10:11], v[86:87], v[24:25] op_sel:[1,0,0] op_sel_hi:[1,1,1]
	v_pk_fma_f32 v[24:25], v[8:9], v[88:89], v[24:25] op_sel:[0,0,0] op_sel_hi:[0,1,1]
	v_pk_fma_f32 v[24:25], v[8:9], v[90:91], v[24:25] op_sel:[1,0,0] op_sel_hi:[1,1,1]
	v_pk_fma_f32 v[16:17], v[92:93], v[160:161], v[10:11] op_sel:[0,1,0] op_sel_hi:[1,1,1]
	v_pk_fma_f32 v[18:19], v[94:95], v[160:161], v[8:9] op_sel:[0,1,0] op_sel_hi:[1,1,1]
	v_add_f32_dpp v15, v24, v24 row_ror:8 row_mask:0xf bank_mask:0xf bound_ctrl:1
	v_add_f32_dpp v32, v25, v25 row_ror:8 row_mask:0xf bank_mask:0xf bound_ctrl:1
	ds_read_b128 v[124:127], v48 offset:15360
	v_add_f32_dpp v15, v15, v15 row_ror:4 row_mask:0xf bank_mask:0xf bound_ctrl:1
	ds_read_b128 v[128:131], v48 offset:15616
	ds_read_b128 v[132:135], v48 offset:15872
	v_add_f32_dpp v15, v15, v15 row_ror:2 row_mask:0xf bank_mask:0xf bound_ctrl:1
	ds_read_b128 v[136:139], v48 offset:16128
	ds_read_b128 v[156:159], v49 offset:64
	v_add_f32_dpp v30, v15, v15 row_ror:1 row_mask:0xf bank_mask:0xf bound_ctrl:1
	v_pk_fma_f32 v[10:11], v[96:97], v[30:31], v[16:17] op_sel_hi:[1,0,1] neg_lo:[0,1,0] neg_hi:[0,1,0]
	v_pk_fma_f32 v[8:9], v[98:99], v[30:31], v[18:19] op_sel_hi:[1,0,1] neg_lo:[0,1,0] neg_hi:[0,1,0]
	v_pk_mul_f32 v[24:25], v[10:11], v[100:101] op_sel:[0,0] op_sel_hi:[0,1]
	v_pk_fma_f32 v[24:25], v[10:11], v[102:103], v[24:25] op_sel:[1,0,0] op_sel_hi:[1,1,1]
	v_pk_fma_f32 v[24:25], v[8:9], v[104:105], v[24:25] op_sel:[0,0,0] op_sel_hi:[0,1,1]
	v_pk_fma_f32 v[24:25], v[8:9], v[106:107], v[24:25] op_sel:[1,0,0] op_sel_hi:[1,1,1]
	v_pk_fma_f32 v[16:17], v[108:109], v[162:163], v[10:11] op_sel_hi:[1,0,1]
	v_pk_fma_f32 v[18:19], v[110:111], v[162:163], v[8:9] op_sel_hi:[1,0,1]
	v_add_f32_dpp v15, v24, v24 row_ror:8 row_mask:0xf bank_mask:0xf bound_ctrl:1
	v_add_f32_dpp v33, v25, v25 row_ror:8 row_mask:0xf bank_mask:0xf bound_ctrl:1
	ds_read_b128 v[76:79], v48 offset:16384
	v_add_f32_dpp v15, v15, v15 row_ror:4 row_mask:0xf bank_mask:0xf bound_ctrl:1
	ds_read_b128 v[80:83], v48 offset:16640
	ds_read_b128 v[84:87], v48 offset:16896
	v_add_f32_dpp v15, v15, v15 row_ror:2 row_mask:0xf bank_mask:0xf bound_ctrl:1
	ds_read_b128 v[88:91], v48 offset:17152
	ds_read_b128 v[144:147], v48 offset:33280
	ds_write2st64_b32 v50, v32, v33 offset0:24 offset1:26
	v_add_f32_dpp v30, v15, v15 row_ror:1 row_mask:0xf bank_mask:0xf bound_ctrl:1
	s_waitcnt lgkmcnt(5)
	v_pk_fma_f32 v[10:11], v[112:113], v[30:31], v[16:17] op_sel_hi:[1,0,1] neg_lo:[0,1,0] neg_hi:[0,1,0]
	v_pk_fma_f32 v[8:9], v[114:115], v[30:31], v[18:19] op_sel_hi:[1,0,1] neg_lo:[0,1,0] neg_hi:[0,1,0]
	v_pk_mul_f32 v[24:25], v[10:11], v[116:117] op_sel:[0,0] op_sel_hi:[0,1]
	v_pk_fma_f32 v[24:25], v[10:11], v[118:119], v[24:25] op_sel:[1,0,0] op_sel_hi:[1,1,1]
	v_pk_fma_f32 v[24:25], v[8:9], v[120:121], v[24:25] op_sel:[0,0,0] op_sel_hi:[0,1,1]
	v_pk_fma_f32 v[24:25], v[8:9], v[122:123], v[24:25] op_sel:[1,0,0] op_sel_hi:[1,1,1]
	v_pk_fma_f32 v[16:17], v[124:125], v[162:163], v[10:11] op_sel:[0,1,0] op_sel_hi:[1,1,1]
	v_pk_fma_f32 v[18:19], v[126:127], v[162:163], v[8:9] op_sel:[0,1,0] op_sel_hi:[1,1,1]
	v_add_f32_dpp v15, v24, v24 row_ror:8 row_mask:0xf bank_mask:0xf bound_ctrl:1
	v_add_f32_dpp v32, v25, v25 row_ror:8 row_mask:0xf bank_mask:0xf bound_ctrl:1
	ds_read_b128 v[92:95], v48 offset:17408
	v_add_f32_dpp v15, v15, v15 row_ror:4 row_mask:0xf bank_mask:0xf bound_ctrl:1
	ds_read_b128 v[96:99], v48 offset:17664
	ds_read_b128 v[100:103], v48 offset:17920
	v_add_f32_dpp v15, v15, v15 row_ror:2 row_mask:0xf bank_mask:0xf bound_ctrl:1
	ds_read_b128 v[104:107], v48 offset:18176
	s_nop 0
	v_add_f32_dpp v30, v15, v15 row_ror:1 row_mask:0xf bank_mask:0xf bound_ctrl:1
	v_pk_fma_f32 v[10:11], v[128:129], v[30:31], v[16:17] op_sel_hi:[1,0,1] neg_lo:[0,1,0] neg_hi:[0,1,0]
	v_pk_fma_f32 v[8:9], v[130:131], v[30:31], v[18:19] op_sel_hi:[1,0,1] neg_lo:[0,1,0] neg_hi:[0,1,0]
	v_pk_mul_f32 v[24:25], v[10:11], v[132:133] op_sel:[0,0] op_sel_hi:[0,1]
	v_pk_fma_f32 v[24:25], v[10:11], v[134:135], v[24:25] op_sel:[1,0,0] op_sel_hi:[1,1,1]
	v_pk_fma_f32 v[24:25], v[8:9], v[136:137], v[24:25] op_sel:[0,0,0] op_sel_hi:[0,1,1]
	v_pk_fma_f32 v[24:25], v[8:9], v[138:139], v[24:25] op_sel:[1,0,0] op_sel_hi:[1,1,1]
	s_nop 1
	v_add_f32_dpp v33, v25, v25 row_ror:8 row_mask:0xf bank_mask:0xf bound_ctrl:1
	ds_write2st64_b32 v50, v32, v33 offset0:28 offset1:30
	v_pk_mul_f32 v[10:11], v[10:11], v[140:141]
	v_pk_mul_f32 v[8:9], v[8:9], v[142:143]
	s_waitcnt lgkmcnt(6)
	v_pk_mul_f32 v[24:25], v[10:11], v[144:145]
	v_pk_fma_f32 v[24:25], v[8:9], v[146:147], v[24:25]
	v_add_f32_e32 v24, v24, v25
	v_pk_fma_f32 v[16:17], v[76:77], v[156:157], v[10:11] op_sel_hi:[1,0,1]
	v_pk_fma_f32 v[18:19], v[78:79], v[156:157], v[8:9] op_sel_hi:[1,0,1]
	v_add_f32_dpp v15, v24, v24 row_ror:8 row_mask:0xf bank_mask:0xf bound_ctrl:1
	ds_read_b128 v[108:111], v48 offset:18432
	ds_read_b128 v[112:115], v48 offset:18688
	v_add_f32_dpp v15, v15, v15 row_ror:4 row_mask:0xf bank_mask:0xf bound_ctrl:1
	ds_read_b128 v[116:119], v48 offset:18944
	ds_read_b128 v[120:123], v48 offset:19200
	v_add_f32_dpp v15, v15, v15 row_ror:2 row_mask:0xf bank_mask:0xf bound_ctrl:1
	s_nop 1
	v_add_f32_dpp v30, v15, v15 row_ror:1 row_mask:0xf bank_mask:0xf bound_ctrl:1
	s_waitcnt lgkmcnt(3)
	v_pk_fma_f32 v[10:11], v[80:81], v[30:31], v[16:17] op_sel_hi:[1,0,1] neg_lo:[0,1,0] neg_hi:[0,1,0]
	v_pk_fma_f32 v[8:9], v[82:83], v[30:31], v[18:19] op_sel_hi:[1,0,1] neg_lo:[0,1,0] neg_hi:[0,1,0]
	v_pk_mul_f32 v[24:25], v[10:11], v[84:85] op_sel:[0,0] op_sel_hi:[0,1]
	v_pk_fma_f32 v[24:25], v[10:11], v[86:87], v[24:25] op_sel:[1,0,0] op_sel_hi:[1,1,1]
	v_pk_fma_f32 v[24:25], v[8:9], v[88:89], v[24:25] op_sel:[0,0,0] op_sel_hi:[0,1,1]
	v_pk_fma_f32 v[24:25], v[8:9], v[90:91], v[24:25] op_sel:[1,0,0] op_sel_hi:[1,1,1]
	v_pk_fma_f32 v[16:17], v[92:93], v[156:157], v[10:11] op_sel:[0,1,0] op_sel_hi:[1,1,1]
	v_pk_fma_f32 v[18:19], v[94:95], v[156:157], v[8:9] op_sel:[0,1,0] op_sel_hi:[1,1,1]
	v_add_f32_dpp v15, v24, v24 row_ror:8 row_mask:0xf bank_mask:0xf bound_ctrl:1
	v_add_f32_dpp v32, v25, v25 row_ror:8 row_mask:0xf bank_mask:0xf bound_ctrl:1
	ds_read_b128 v[124:127], v48 offset:19456
	v_add_f32_dpp v15, v15, v15 row_ror:4 row_mask:0xf bank_mask:0xf bound_ctrl:1
	ds_read_b128 v[128:131], v48 offset:19712
	ds_read_b128 v[132:135], v48 offset:19968
	v_add_f32_dpp v15, v15, v15 row_ror:2 row_mask:0xf bank_mask:0xf bound_ctrl:1
	ds_read_b128 v[136:139], v48 offset:20224
	ds_read_b128 v[160:163], v49 offset:80
	v_add_f32_dpp v30, v15, v15 row_ror:1 row_mask:0xf bank_mask:0xf bound_ctrl:1
	v_pk_fma_f32 v[10:11], v[96:97], v[30:31], v[16:17] op_sel_hi:[1,0,1] neg_lo:[0,1,0] neg_hi:[0,1,0]
	v_pk_fma_f32 v[8:9], v[98:99], v[30:31], v[18:19] op_sel_hi:[1,0,1] neg_lo:[0,1,0] neg_hi:[0,1,0]
	v_pk_mul_f32 v[24:25], v[10:11], v[100:101] op_sel:[0,0] op_sel_hi:[0,1]
	v_pk_fma_f32 v[24:25], v[10:11], v[102:103], v[24:25] op_sel:[1,0,0] op_sel_hi:[1,1,1]
	v_pk_fma_f32 v[24:25], v[8:9], v[104:105], v[24:25] op_sel:[0,0,0] op_sel_hi:[0,1,1]
	v_pk_fma_f32 v[24:25], v[8:9], v[106:107], v[24:25] op_sel:[1,0,0] op_sel_hi:[1,1,1]
	v_pk_fma_f32 v[16:17], v[108:109], v[158:159], v[10:11] op_sel_hi:[1,0,1]
	v_pk_fma_f32 v[18:19], v[110:111], v[158:159], v[8:9] op_sel_hi:[1,0,1]
	v_add_f32_dpp v15, v24, v24 row_ror:8 row_mask:0xf bank_mask:0xf bound_ctrl:1
	v_add_f32_dpp v33, v25, v25 row_ror:8 row_mask:0xf bank_mask:0xf bound_ctrl:1
	ds_read_b128 v[76:79], v48 offset:20480
	v_add_f32_dpp v15, v15, v15 row_ror:4 row_mask:0xf bank_mask:0xf bound_ctrl:1
	ds_read_b128 v[80:83], v48 offset:20736
	ds_read_b128 v[84:87], v48 offset:20992
	v_add_f32_dpp v15, v15, v15 row_ror:2 row_mask:0xf bank_mask:0xf bound_ctrl:1
	ds_read_b128 v[88:91], v48 offset:21248
	ds_write2st64_b32 v50, v32, v33 offset0:32 offset1:34
	v_add_f32_dpp v30, v15, v15 row_ror:1 row_mask:0xf bank_mask:0xf bound_ctrl:1
	s_waitcnt lgkmcnt(4)
	v_pk_fma_f32 v[10:11], v[112:113], v[30:31], v[16:17] op_sel_hi:[1,0,1] neg_lo:[0,1,0] neg_hi:[0,1,0]
	v_pk_fma_f32 v[8:9], v[114:115], v[30:31], v[18:19] op_sel_hi:[1,0,1] neg_lo:[0,1,0] neg_hi:[0,1,0]
	v_pk_mul_f32 v[24:25], v[10:11], v[116:117] op_sel:[0,0] op_sel_hi:[0,1]
	v_pk_fma_f32 v[24:25], v[10:11], v[118:119], v[24:25] op_sel:[1,0,0] op_sel_hi:[1,1,1]
	v_pk_fma_f32 v[24:25], v[8:9], v[120:121], v[24:25] op_sel:[0,0,0] op_sel_hi:[0,1,1]
	v_pk_fma_f32 v[24:25], v[8:9], v[122:123], v[24:25] op_sel:[1,0,0] op_sel_hi:[1,1,1]
	v_pk_fma_f32 v[16:17], v[124:125], v[158:159], v[10:11] op_sel:[0,1,0] op_sel_hi:[1,1,1]
	v_pk_fma_f32 v[18:19], v[126:127], v[158:159], v[8:9] op_sel:[0,1,0] op_sel_hi:[1,1,1]
	v_add_f32_dpp v15, v24, v24 row_ror:8 row_mask:0xf bank_mask:0xf bound_ctrl:1
	v_add_f32_dpp v32, v25, v25 row_ror:8 row_mask:0xf bank_mask:0xf bound_ctrl:1
	ds_read_b128 v[92:95], v48 offset:21504
	v_add_f32_dpp v15, v15, v15 row_ror:4 row_mask:0xf bank_mask:0xf bound_ctrl:1
	ds_read_b128 v[96:99], v48 offset:21760
	ds_read_b128 v[100:103], v48 offset:22016
	v_add_f32_dpp v15, v15, v15 row_ror:2 row_mask:0xf bank_mask:0xf bound_ctrl:1
	ds_read_b128 v[104:107], v48 offset:22272
	s_nop 0
	v_add_f32_dpp v30, v15, v15 row_ror:1 row_mask:0xf bank_mask:0xf bound_ctrl:1
	v_pk_fma_f32 v[10:11], v[128:129], v[30:31], v[16:17] op_sel_hi:[1,0,1] neg_lo:[0,1,0] neg_hi:[0,1,0]
	v_pk_fma_f32 v[8:9], v[130:131], v[30:31], v[18:19] op_sel_hi:[1,0,1] neg_lo:[0,1,0] neg_hi:[0,1,0]
	v_pk_mul_f32 v[24:25], v[10:11], v[132:133] op_sel:[0,0] op_sel_hi:[0,1]
	v_pk_fma_f32 v[24:25], v[10:11], v[134:135], v[24:25] op_sel:[1,0,0] op_sel_hi:[1,1,1]
	v_pk_fma_f32 v[24:25], v[8:9], v[136:137], v[24:25] op_sel:[0,0,0] op_sel_hi:[0,1,1]
	v_pk_fma_f32 v[24:25], v[8:9], v[138:139], v[24:25] op_sel:[1,0,0] op_sel_hi:[1,1,1]
	v_pk_fma_f32 v[16:17], v[76:77], v[160:161], v[10:11] op_sel_hi:[1,0,1]
	v_pk_fma_f32 v[18:19], v[78:79], v[160:161], v[8:9] op_sel_hi:[1,0,1]
	v_add_f32_dpp v15, v24, v24 row_ror:8 row_mask:0xf bank_mask:0xf bound_ctrl:1
	v_add_f32_dpp v33, v25, v25 row_ror:8 row_mask:0xf bank_mask:0xf bound_ctrl:1
	ds_read_b128 v[108:111], v48 offset:22528
	v_add_f32_dpp v15, v15, v15 row_ror:4 row_mask:0xf bank_mask:0xf bound_ctrl:1
	ds_read_b128 v[112:115], v48 offset:22784
	ds_read_b128 v[116:119], v48 offset:23040
	v_add_f32_dpp v15, v15, v15 row_ror:2 row_mask:0xf bank_mask:0xf bound_ctrl:1
	ds_read_b128 v[120:123], v48 offset:23296
	ds_read_b128 v[140:143], v48 offset:34304
	ds_write2st64_b32 v50, v32, v33 offset0:36 offset1:38
	v_add_f32_dpp v30, v15, v15 row_ror:1 row_mask:0xf bank_mask:0xf bound_ctrl:1
	s_waitcnt lgkmcnt(5)
	v_pk_fma_f32 v[10:11], v[80:81], v[30:31], v[16:17] op_sel_hi:[1,0,1] neg_lo:[0,1,0] neg_hi:[0,1,0]
	v_pk_fma_f32 v[8:9], v[82:83], v[30:31], v[18:19] op_sel_hi:[1,0,1] neg_lo:[0,1,0] neg_hi:[0,1,0]
	v_pk_mul_f32 v[24:25], v[10:11], v[84:85] op_sel:[0,0] op_sel_hi:[0,1]
	v_pk_fma_f32 v[24:25], v[10:11], v[86:87], v[24:25] op_sel:[1,0,0] op_sel_hi:[1,1,1]
	v_pk_fma_f32 v[24:25], v[8:9], v[88:89], v[24:25] op_sel:[0,0,0] op_sel_hi:[0,1,1]
	v_pk_fma_f32 v[24:25], v[8:9], v[90:91], v[24:25] op_sel:[1,0,0] op_sel_hi:[1,1,1]
	v_pk_fma_f32 v[16:17], v[92:93], v[160:161], v[10:11] op_sel:[0,1,0] op_sel_hi:[1,1,1]
	v_pk_fma_f32 v[18:19], v[94:95], v[160:161], v[8:9] op_sel:[0,1,0] op_sel_hi:[1,1,1]
	v_add_f32_dpp v15, v24, v24 row_ror:8 row_mask:0xf bank_mask:0xf bound_ctrl:1
	v_add_f32_dpp v32, v25, v25 row_ror:8 row_mask:0xf bank_mask:0xf bound_ctrl:1
	ds_read_b128 v[124:127], v48 offset:23552
	v_add_f32_dpp v15, v15, v15 row_ror:4 row_mask:0xf bank_mask:0xf bound_ctrl:1
	ds_read_b128 v[128:131], v48 offset:23808
	ds_read_b128 v[132:135], v48 offset:24064
	v_add_f32_dpp v15, v15, v15 row_ror:2 row_mask:0xf bank_mask:0xf bound_ctrl:1
	ds_read_b128 v[136:139], v48 offset:24320
	ds_read_b128 v[156:159], v49 offset:96
	v_add_f32_dpp v30, v15, v15 row_ror:1 row_mask:0xf bank_mask:0xf bound_ctrl:1
	v_pk_fma_f32 v[10:11], v[96:97], v[30:31], v[16:17] op_sel_hi:[1,0,1] neg_lo:[0,1,0] neg_hi:[0,1,0]
	v_pk_fma_f32 v[8:9], v[98:99], v[30:31], v[18:19] op_sel_hi:[1,0,1] neg_lo:[0,1,0] neg_hi:[0,1,0]
	v_pk_mul_f32 v[24:25], v[10:11], v[100:101] op_sel:[0,0] op_sel_hi:[0,1]
	v_pk_fma_f32 v[24:25], v[10:11], v[102:103], v[24:25] op_sel:[1,0,0] op_sel_hi:[1,1,1]
	v_pk_fma_f32 v[24:25], v[8:9], v[104:105], v[24:25] op_sel:[0,0,0] op_sel_hi:[0,1,1]
	v_pk_fma_f32 v[24:25], v[8:9], v[106:107], v[24:25] op_sel:[1,0,0] op_sel_hi:[1,1,1]
	v_pk_fma_f32 v[16:17], v[108:109], v[162:163], v[10:11] op_sel_hi:[1,0,1]
	v_pk_fma_f32 v[18:19], v[110:111], v[162:163], v[8:9] op_sel_hi:[1,0,1]
	v_add_f32_dpp v15, v24, v24 row_ror:8 row_mask:0xf bank_mask:0xf bound_ctrl:1
	v_add_f32_dpp v33, v25, v25 row_ror:8 row_mask:0xf bank_mask:0xf bound_ctrl:1
	ds_read_b128 v[76:79], v48 offset:24576
	v_add_f32_dpp v15, v15, v15 row_ror:4 row_mask:0xf bank_mask:0xf bound_ctrl:1
	ds_read_b128 v[80:83], v48 offset:24832
	ds_read_b128 v[84:87], v48 offset:25088
	v_add_f32_dpp v15, v15, v15 row_ror:2 row_mask:0xf bank_mask:0xf bound_ctrl:1
	ds_read_b128 v[88:91], v48 offset:25344
	ds_read_b128 v[144:147], v48 offset:33536
	ds_write2st64_b32 v50, v32, v33 offset0:40 offset1:42
	v_add_f32_dpp v30, v15, v15 row_ror:1 row_mask:0xf bank_mask:0xf bound_ctrl:1
	s_waitcnt lgkmcnt(5)
	v_pk_fma_f32 v[10:11], v[112:113], v[30:31], v[16:17] op_sel_hi:[1,0,1] neg_lo:[0,1,0] neg_hi:[0,1,0]
	v_pk_fma_f32 v[8:9], v[114:115], v[30:31], v[18:19] op_sel_hi:[1,0,1] neg_lo:[0,1,0] neg_hi:[0,1,0]
	v_pk_mul_f32 v[24:25], v[10:11], v[116:117] op_sel:[0,0] op_sel_hi:[0,1]
	v_pk_fma_f32 v[24:25], v[10:11], v[118:119], v[24:25] op_sel:[1,0,0] op_sel_hi:[1,1,1]
	v_pk_fma_f32 v[24:25], v[8:9], v[120:121], v[24:25] op_sel:[0,0,0] op_sel_hi:[0,1,1]
	v_pk_fma_f32 v[24:25], v[8:9], v[122:123], v[24:25] op_sel:[1,0,0] op_sel_hi:[1,1,1]
	v_pk_fma_f32 v[16:17], v[124:125], v[162:163], v[10:11] op_sel:[0,1,0] op_sel_hi:[1,1,1]
	v_pk_fma_f32 v[18:19], v[126:127], v[162:163], v[8:9] op_sel:[0,1,0] op_sel_hi:[1,1,1]
	v_add_f32_dpp v15, v24, v24 row_ror:8 row_mask:0xf bank_mask:0xf bound_ctrl:1
	v_add_f32_dpp v32, v25, v25 row_ror:8 row_mask:0xf bank_mask:0xf bound_ctrl:1
	ds_read_b128 v[92:95], v48 offset:25600
	v_add_f32_dpp v15, v15, v15 row_ror:4 row_mask:0xf bank_mask:0xf bound_ctrl:1
	ds_read_b128 v[96:99], v48 offset:25856
	ds_read_b128 v[100:103], v48 offset:26112
	v_add_f32_dpp v15, v15, v15 row_ror:2 row_mask:0xf bank_mask:0xf bound_ctrl:1
	ds_read_b128 v[104:107], v48 offset:26368
	s_nop 0
	v_add_f32_dpp v30, v15, v15 row_ror:1 row_mask:0xf bank_mask:0xf bound_ctrl:1
	v_pk_fma_f32 v[10:11], v[128:129], v[30:31], v[16:17] op_sel_hi:[1,0,1] neg_lo:[0,1,0] neg_hi:[0,1,0]
	v_pk_fma_f32 v[8:9], v[130:131], v[30:31], v[18:19] op_sel_hi:[1,0,1] neg_lo:[0,1,0] neg_hi:[0,1,0]
	v_pk_mul_f32 v[24:25], v[10:11], v[132:133] op_sel:[0,0] op_sel_hi:[0,1]
	v_pk_fma_f32 v[24:25], v[10:11], v[134:135], v[24:25] op_sel:[1,0,0] op_sel_hi:[1,1,1]
	v_pk_fma_f32 v[24:25], v[8:9], v[136:137], v[24:25] op_sel:[0,0,0] op_sel_hi:[0,1,1]
	v_pk_fma_f32 v[24:25], v[8:9], v[138:139], v[24:25] op_sel:[1,0,0] op_sel_hi:[1,1,1]
	s_nop 1
	v_add_f32_dpp v33, v25, v25 row_ror:8 row_mask:0xf bank_mask:0xf bound_ctrl:1
	ds_write2st64_b32 v50, v32, v33 offset0:44 offset1:46
	v_pk_mul_f32 v[10:11], v[10:11], v[140:141]
	v_pk_mul_f32 v[8:9], v[8:9], v[142:143]
	s_waitcnt lgkmcnt(6)
	v_pk_mul_f32 v[24:25], v[10:11], v[144:145]
	v_pk_fma_f32 v[24:25], v[8:9], v[146:147], v[24:25]
	v_add_f32_e32 v24, v24, v25
	v_pk_fma_f32 v[16:17], v[76:77], v[156:157], v[10:11] op_sel_hi:[1,0,1]
	v_pk_fma_f32 v[18:19], v[78:79], v[156:157], v[8:9] op_sel_hi:[1,0,1]
	v_add_f32_dpp v15, v24, v24 row_ror:8 row_mask:0xf bank_mask:0xf bound_ctrl:1
	ds_read_b128 v[108:111], v48 offset:26624
	ds_read_b128 v[112:115], v48 offset:26880
	v_add_f32_dpp v15, v15, v15 row_ror:4 row_mask:0xf bank_mask:0xf bound_ctrl:1
	ds_read_b128 v[116:119], v48 offset:27136
	ds_read_b128 v[120:123], v48 offset:27392
	v_add_f32_dpp v15, v15, v15 row_ror:2 row_mask:0xf bank_mask:0xf bound_ctrl:1
	s_nop 1
	v_add_f32_dpp v30, v15, v15 row_ror:1 row_mask:0xf bank_mask:0xf bound_ctrl:1
	s_waitcnt lgkmcnt(3)
	v_pk_fma_f32 v[10:11], v[80:81], v[30:31], v[16:17] op_sel_hi:[1,0,1] neg_lo:[0,1,0] neg_hi:[0,1,0]
	v_pk_fma_f32 v[8:9], v[82:83], v[30:31], v[18:19] op_sel_hi:[1,0,1] neg_lo:[0,1,0] neg_hi:[0,1,0]
	v_pk_mul_f32 v[24:25], v[10:11], v[84:85] op_sel:[0,0] op_sel_hi:[0,1]
	v_pk_fma_f32 v[24:25], v[10:11], v[86:87], v[24:25] op_sel:[1,0,0] op_sel_hi:[1,1,1]
	v_pk_fma_f32 v[24:25], v[8:9], v[88:89], v[24:25] op_sel:[0,0,0] op_sel_hi:[0,1,1]
	v_pk_fma_f32 v[24:25], v[8:9], v[90:91], v[24:25] op_sel:[1,0,0] op_sel_hi:[1,1,1]
	v_pk_fma_f32 v[16:17], v[92:93], v[156:157], v[10:11] op_sel:[0,1,0] op_sel_hi:[1,1,1]
	v_pk_fma_f32 v[18:19], v[94:95], v[156:157], v[8:9] op_sel:[0,1,0] op_sel_hi:[1,1,1]
	v_add_f32_dpp v15, v24, v24 row_ror:8 row_mask:0xf bank_mask:0xf bound_ctrl:1
	v_add_f32_dpp v32, v25, v25 row_ror:8 row_mask:0xf bank_mask:0xf bound_ctrl:1
	ds_read_b128 v[124:127], v48 offset:27648
	v_add_f32_dpp v15, v15, v15 row_ror:4 row_mask:0xf bank_mask:0xf bound_ctrl:1
	ds_read_b128 v[128:131], v48 offset:27904
	ds_read_b128 v[132:135], v48 offset:28160
	v_add_f32_dpp v15, v15, v15 row_ror:2 row_mask:0xf bank_mask:0xf bound_ctrl:1
	ds_read_b128 v[136:139], v48 offset:28416
	ds_read_b128 v[160:163], v49 offset:112
	v_add_f32_dpp v30, v15, v15 row_ror:1 row_mask:0xf bank_mask:0xf bound_ctrl:1
	v_pk_fma_f32 v[10:11], v[96:97], v[30:31], v[16:17] op_sel_hi:[1,0,1] neg_lo:[0,1,0] neg_hi:[0,1,0]
	v_pk_fma_f32 v[8:9], v[98:99], v[30:31], v[18:19] op_sel_hi:[1,0,1] neg_lo:[0,1,0] neg_hi:[0,1,0]
	v_pk_mul_f32 v[24:25], v[10:11], v[100:101] op_sel:[0,0] op_sel_hi:[0,1]
	v_pk_fma_f32 v[24:25], v[10:11], v[102:103], v[24:25] op_sel:[1,0,0] op_sel_hi:[1,1,1]
	v_pk_fma_f32 v[24:25], v[8:9], v[104:105], v[24:25] op_sel:[0,0,0] op_sel_hi:[0,1,1]
	v_pk_fma_f32 v[24:25], v[8:9], v[106:107], v[24:25] op_sel:[1,0,0] op_sel_hi:[1,1,1]
	v_pk_fma_f32 v[16:17], v[108:109], v[158:159], v[10:11] op_sel_hi:[1,0,1]
	v_pk_fma_f32 v[18:19], v[110:111], v[158:159], v[8:9] op_sel_hi:[1,0,1]
	v_add_f32_dpp v15, v24, v24 row_ror:8 row_mask:0xf bank_mask:0xf bound_ctrl:1
	v_add_f32_dpp v33, v25, v25 row_ror:8 row_mask:0xf bank_mask:0xf bound_ctrl:1
	ds_read_b128 v[76:79], v48 offset:28672
	v_add_f32_dpp v15, v15, v15 row_ror:4 row_mask:0xf bank_mask:0xf bound_ctrl:1
	ds_read_b128 v[80:83], v48 offset:28928
	ds_read_b128 v[84:87], v48 offset:29184
	v_add_f32_dpp v15, v15, v15 row_ror:2 row_mask:0xf bank_mask:0xf bound_ctrl:1
	ds_read_b128 v[88:91], v48 offset:29440
	ds_write2st64_b32 v50, v32, v33 offset0:48 offset1:50
	v_add_f32_dpp v30, v15, v15 row_ror:1 row_mask:0xf bank_mask:0xf bound_ctrl:1
	ds_read_b128 v[56:59], v52
	s_waitcnt lgkmcnt(5)
	v_pk_fma_f32 v[10:11], v[112:113], v[30:31], v[16:17] op_sel_hi:[1,0,1] neg_lo:[0,1,0] neg_hi:[0,1,0]
	v_pk_fma_f32 v[8:9], v[114:115], v[30:31], v[18:19] op_sel_hi:[1,0,1] neg_lo:[0,1,0] neg_hi:[0,1,0]
	v_pk_mul_f32 v[24:25], v[10:11], v[116:117] op_sel:[0,0] op_sel_hi:[0,1]
	v_pk_fma_f32 v[24:25], v[10:11], v[118:119], v[24:25] op_sel:[1,0,0] op_sel_hi:[1,1,1]
	v_pk_fma_f32 v[24:25], v[8:9], v[120:121], v[24:25] op_sel:[0,0,0] op_sel_hi:[0,1,1]
	v_pk_fma_f32 v[24:25], v[8:9], v[122:123], v[24:25] op_sel:[1,0,0] op_sel_hi:[1,1,1]
	v_pk_fma_f32 v[16:17], v[124:125], v[158:159], v[10:11] op_sel:[0,1,0] op_sel_hi:[1,1,1]
	v_pk_fma_f32 v[18:19], v[126:127], v[158:159], v[8:9] op_sel:[0,1,0] op_sel_hi:[1,1,1]
	v_add_f32_dpp v15, v24, v24 row_ror:8 row_mask:0xf bank_mask:0xf bound_ctrl:1
	v_add_f32_dpp v32, v25, v25 row_ror:8 row_mask:0xf bank_mask:0xf bound_ctrl:1
	ds_read_b128 v[92:95], v48 offset:29696
	v_add_f32_dpp v15, v15, v15 row_ror:4 row_mask:0xf bank_mask:0xf bound_ctrl:1
	ds_read_b128 v[96:99], v48 offset:29952
	ds_read_b128 v[100:103], v48 offset:30208
	v_add_f32_dpp v15, v15, v15 row_ror:2 row_mask:0xf bank_mask:0xf bound_ctrl:1
	ds_read_b128 v[104:107], v48 offset:30464
	s_nop 0
	v_add_f32_dpp v30, v15, v15 row_ror:1 row_mask:0xf bank_mask:0xf bound_ctrl:1
	s_waitcnt lgkmcnt(4)
	v_min_u32_e32 v56, v56, v57
	v_min3_u32 v56, v56, v58, v59
	v_pk_fma_f32 v[10:11], v[128:129], v[30:31], v[16:17] op_sel_hi:[1,0,1] neg_lo:[0,1,0] neg_hi:[0,1,0]
	v_pk_fma_f32 v[8:9], v[130:131], v[30:31], v[18:19] op_sel_hi:[1,0,1] neg_lo:[0,1,0] neg_hi:[0,1,0]
	v_pk_mul_f32 v[24:25], v[10:11], v[132:133] op_sel:[0,0] op_sel_hi:[0,1]
	v_pk_fma_f32 v[24:25], v[10:11], v[134:135], v[24:25] op_sel:[1,0,0] op_sel_hi:[1,1,1]
	v_pk_fma_f32 v[24:25], v[8:9], v[136:137], v[24:25] op_sel:[0,0,0] op_sel_hi:[0,1,1]
	v_pk_fma_f32 v[24:25], v[8:9], v[138:139], v[24:25] op_sel:[1,0,0] op_sel_hi:[1,1,1]
	v_pk_fma_f32 v[16:17], v[76:77], v[160:161], v[10:11] op_sel_hi:[1,0,1]
	v_pk_fma_f32 v[18:19], v[78:79], v[160:161], v[8:9] op_sel_hi:[1,0,1]
	v_add_f32_dpp v15, v24, v24 row_ror:8 row_mask:0xf bank_mask:0xf bound_ctrl:1
	v_add_f32_dpp v33, v25, v25 row_ror:8 row_mask:0xf bank_mask:0xf bound_ctrl:1
	ds_read_b128 v[108:111], v48 offset:30720
	v_add_f32_dpp v15, v15, v15 row_ror:4 row_mask:0xf bank_mask:0xf bound_ctrl:1
	ds_read_b128 v[112:115], v48 offset:30976
	ds_read_b128 v[116:119], v48 offset:31232
	v_add_f32_dpp v15, v15, v15 row_ror:2 row_mask:0xf bank_mask:0xf bound_ctrl:1
	ds_read_b128 v[120:123], v48 offset:31488
	ds_read_b128 v[140:143], v48 offset:34560
	ds_write2st64_b32 v50, v32, v33 offset0:52 offset1:54
	v_add_f32_dpp v30, v15, v15 row_ror:1 row_mask:0xf bank_mask:0xf bound_ctrl:1
	s_waitcnt lgkmcnt(5)
	v_pk_fma_f32 v[10:11], v[80:81], v[30:31], v[16:17] op_sel_hi:[1,0,1] neg_lo:[0,1,0] neg_hi:[0,1,0]
	v_pk_fma_f32 v[8:9], v[82:83], v[30:31], v[18:19] op_sel_hi:[1,0,1] neg_lo:[0,1,0] neg_hi:[0,1,0]
	v_pk_mul_f32 v[24:25], v[10:11], v[84:85] op_sel:[0,0] op_sel_hi:[0,1]
	v_pk_fma_f32 v[24:25], v[10:11], v[86:87], v[24:25] op_sel:[1,0,0] op_sel_hi:[1,1,1]
	v_pk_fma_f32 v[24:25], v[8:9], v[88:89], v[24:25] op_sel:[0,0,0] op_sel_hi:[0,1,1]
	v_pk_fma_f32 v[24:25], v[8:9], v[90:91], v[24:25] op_sel:[1,0,0] op_sel_hi:[1,1,1]
	v_pk_fma_f32 v[16:17], v[92:93], v[160:161], v[10:11] op_sel:[0,1,0] op_sel_hi:[1,1,1]
	v_pk_fma_f32 v[18:19], v[94:95], v[160:161], v[8:9] op_sel:[0,1,0] op_sel_hi:[1,1,1]
	v_add_f32_dpp v15, v24, v24 row_ror:8 row_mask:0xf bank_mask:0xf bound_ctrl:1
	v_add_f32_dpp v32, v25, v25 row_ror:8 row_mask:0xf bank_mask:0xf bound_ctrl:1
	ds_read_b128 v[124:127], v48 offset:31744
	v_add_f32_dpp v15, v15, v15 row_ror:4 row_mask:0xf bank_mask:0xf bound_ctrl:1
	ds_read_b128 v[128:131], v48 offset:32000
	ds_read_b128 v[132:135], v48 offset:32256
	v_add_f32_dpp v15, v15, v15 row_ror:2 row_mask:0xf bank_mask:0xf bound_ctrl:1
	ds_read_b128 v[136:139], v48 offset:32512
	s_nop 0
	v_add_f32_dpp v30, v15, v15 row_ror:1 row_mask:0xf bank_mask:0xf bound_ctrl:1
	v_readfirstlane_b32 s54, v56
	s_add_u32 s64, s6, 2
	s_cmp_lt_u32 s54, s64
	s_cbranch_scc1 .Lss_spin_1
.Lss_ok_1:
	v_pk_fma_f32 v[10:11], v[96:97], v[30:31], v[16:17] op_sel_hi:[1,0,1] neg_lo:[0,1,0] neg_hi:[0,1,0]
	v_pk_fma_f32 v[8:9], v[98:99], v[30:31], v[18:19] op_sel_hi:[1,0,1] neg_lo:[0,1,0] neg_hi:[0,1,0]
	v_pk_mul_f32 v[24:25], v[10:11], v[100:101] op_sel:[0,0] op_sel_hi:[0,1]
	v_pk_fma_f32 v[24:25], v[10:11], v[102:103], v[24:25] op_sel:[1,0,0] op_sel_hi:[1,1,1]
	v_pk_fma_f32 v[24:25], v[8:9], v[104:105], v[24:25] op_sel:[0,0,0] op_sel_hi:[0,1,1]
	v_pk_fma_f32 v[24:25], v[8:9], v[106:107], v[24:25] op_sel:[1,0,0] op_sel_hi:[1,1,1]
	v_pk_fma_f32 v[16:17], v[108:109], v[162:163], v[10:11] op_sel_hi:[1,0,1]
	v_pk_fma_f32 v[18:19], v[110:111], v[162:163], v[8:9] op_sel_hi:[1,0,1]
	v_add_f32_dpp v15, v24, v24 row_ror:8 row_mask:0xf bank_mask:0xf bound_ctrl:1
	v_add_f32_dpp v33, v25, v25 row_ror:8 row_mask:0xf bank_mask:0xf bound_ctrl:1
	ds_read_b128 v[76:79], v34 offset:0
	v_add_f32_dpp v15, v15, v15 row_ror:4 row_mask:0xf bank_mask:0xf bound_ctrl:1
	ds_read_b128 v[80:83], v34 offset:256
	ds_read_b128 v[84:87], v34 offset:512
	v_add_f32_dpp v15, v15, v15 row_ror:2 row_mask:0xf bank_mask:0xf bound_ctrl:1
	ds_read_b128 v[88:91], v34 offset:768
	ds_read_b128 v[144:147], v34 offset:32768
	ds_write2st64_b32 v50, v32, v33 offset0:56 offset1:58
	v_add_f32_dpp v30, v15, v15 row_ror:1 row_mask:0xf bank_mask:0xf bound_ctrl:1
	ds_read_b128 v[156:159], v35 offset:0
	s_waitcnt lgkmcnt(6)
	v_pk_fma_f32 v[10:11], v[112:113], v[30:31], v[16:17] op_sel_hi:[1,0,1] neg_lo:[0,1,0] neg_hi:[0,1,0]
	v_pk_fma_f32 v[8:9], v[114:115], v[30:31], v[18:19] op_sel_hi:[1,0,1] neg_lo:[0,1,0] neg_hi:[0,1,0]
	v_pk_mul_f32 v[24:25], v[10:11], v[116:117] op_sel:[0,0] op_sel_hi:[0,1]
	v_pk_fma_f32 v[24:25], v[10:11], v[118:119], v[24:25] op_sel:[1,0,0] op_sel_hi:[1,1,1]
	v_pk_fma_f32 v[24:25], v[8:9], v[120:121], v[24:25] op_sel:[0,0,0] op_sel_hi:[0,1,1]
	v_pk_fma_f32 v[24:25], v[8:9], v[122:123], v[24:25] op_sel:[1,0,0] op_sel_hi:[1,1,1]
	v_pk_fma_f32 v[16:17], v[124:125], v[162:163], v[10:11] op_sel:[0,1,0] op_sel_hi:[1,1,1]
	v_pk_fma_f32 v[18:19], v[126:127], v[162:163], v[8:9] op_sel:[0,1,0] op_sel_hi:[1,1,1]
	v_add_f32_dpp v15, v24, v24 row_ror:8 row_mask:0xf bank_mask:0xf bound_ctrl:1
	v_add_f32_dpp v32, v25, v25 row_ror:8 row_mask:0xf bank_mask:0xf bound_ctrl:1
	ds_read_b128 v[92:95], v34 offset:1024
	v_add_f32_dpp v15, v15, v15 row_ror:4 row_mask:0xf bank_mask:0xf bound_ctrl:1
	ds_read_b128 v[96:99], v34 offset:1280
	ds_read_b128 v[100:103], v34 offset:1536
	v_add_f32_dpp v15, v15, v15 row_ror:2 row_mask:0xf bank_mask:0xf bound_ctrl:1
	ds_read_b128 v[104:107], v34 offset:1792
	s_nop 0
	v_add_f32_dpp v30, v15, v15 row_ror:1 row_mask:0xf bank_mask:0xf bound_ctrl:1
	v_pk_fma_f32 v[10:11], v[128:129], v[30:31], v[16:17] op_sel_hi:[1,0,1] neg_lo:[0,1,0] neg_hi:[0,1,0]
	v_pk_fma_f32 v[8:9], v[130:131], v[30:31], v[18:19] op_sel_hi:[1,0,1] neg_lo:[0,1,0] neg_hi:[0,1,0]
	v_pk_mul_f32 v[24:25], v[10:11], v[132:133] op_sel:[0,0] op_sel_hi:[0,1]
	v_pk_fma_f32 v[24:25], v[10:11], v[134:135], v[24:25] op_sel:[1,0,0] op_sel_hi:[1,1,1]
	v_pk_fma_f32 v[24:25], v[8:9], v[136:137], v[24:25] op_sel:[0,0,0] op_sel_hi:[0,1,1]
	v_pk_fma_f32 v[24:25], v[8:9], v[138:139], v[24:25] op_sel:[1,0,0] op_sel_hi:[1,1,1]
	s_nop 1
	v_add_f32_dpp v33, v25, v25 row_ror:8 row_mask:0xf bank_mask:0xf bound_ctrl:1
	ds_write2st64_b32 v50, v32, v33 offset0:60 offset1:62
	v_pk_mul_f32 v[10:11], v[10:11], v[140:141]
	v_pk_mul_f32 v[8:9], v[8:9], v[142:143]
	s_waitcnt lgkmcnt(7)
	v_pk_mul_f32 v[24:25], v[10:11], v[144:145]
	v_pk_fma_f32 v[24:25], v[8:9], v[146:147], v[24:25]
	v_add_f32_e32 v24, v24, v25
	s_waitcnt lgkmcnt(5)
	v_pk_fma_f32 v[16:17], v[76:77], v[156:157], v[10:11] op_sel_hi:[1,0,1]
	v_pk_fma_f32 v[18:19], v[78:79], v[156:157], v[8:9] op_sel_hi:[1,0,1]
	v_add_f32_dpp v15, v24, v24 row_ror:8 row_mask:0xf bank_mask:0xf bound_ctrl:1
	v_add_u32_e32 v51, 1, v51
	s_add_u32 s6, s6, 1
	v_add_f32_dpp v15, v15, v15 row_ror:4 row_mask:0xf bank_mask:0xf bound_ctrl:1
	ds_write_b32 v53, v51
	ds_read_b128 v[108:111], v34 offset:2048
	v_add_f32_dpp v15, v15, v15 row_ror:2 row_mask:0xf bank_mask:0xf bound_ctrl:1
	ds_read_b128 v[112:115], v34 offset:2304
	ds_read_b128 v[116:119], v34 offset:2560
	v_add_f32_dpp v30, v15, v15 row_ror:1 row_mask:0xf bank_mask:0xf bound_ctrl:1
	ds_read_b128 v[120:123], v34 offset:2816
	s_cmp_lt_u32 s6, 0x100
	s_cbranch_scc1 .Lsc_S_loop
	s_waitcnt lgkmcnt(0)
	s_branch .Lsc_item_end
	s_nop 0
	s_nop 0
	s_nop 0
	s_nop 0
	s_nop 0
	s_nop 0
	s_nop 0
	s_nop 0
	s_nop 0
	s_nop 0
	s_nop 0
	s_nop 0
	s_nop 0
	s_nop 0
	s_nop 0
	s_nop 0
	s_nop 0

.Lsc_G_loop:
	s_sub_u32 s65, s6, 1
	ds_read_b128 v[148:151], v144
	s_waitcnt lgkmcnt(0)
	v_min_u32_e32 v148, v148, v149
	v_min3_u32 v148, v148, v150, v151
	s_nop 1
	v_readfirstlane_b32 s68, v148
	s_cmp_ge_u32 s68, s65
	s_cbranch_scc1 .Lsc_G_gom0
	s_mov_b32 s69, 0x100000
.Lsc_G_pollm0:
	s_sleep 8
	ds_read_b128 v[148:151], v144
	s_waitcnt lgkmcnt(0)
	v_min_u32_e32 v148, v148, v149
	v_min3_u32 v148, v148, v150, v151
	s_sub_u32 s69, s69, 1
	s_nop 1
	v_readfirstlane_b32 s68, v148
	s_cmp_eq_u32 s69, 0
	s_cbranch_scc1 .Lsc_G_gom0
	s_cmp_lt_u32 s68, s65
	s_cbranch_scc1 .Lsc_G_pollm0
.Lsc_G_gom0:
	s_waitcnt vmcnt(10)
	v_lshlrev_b32_e32 v64, 16, v36
	v_and_b32_e32 v65, 0xffff0000, v36
	v_mul_f32_e32 v64, 0x3fb8aa3b, v64
	v_mul_f32_e32 v65, 0x3fb8aa3b, v65
	v_lshlrev_b32_e32 v66, 16, v37
	v_and_b32_e32 v67, 0xffff0000, v37
	v_mul_f32_e32 v66, 0x3fb8aa3b, v66
	v_mul_f32_e32 v67, 0x3fb8aa3b, v67
	v_lshlrev_b32_e32 v68, 16, v38
	v_and_b32_e32 v69, 0xffff0000, v38
	v_mul_f32_e32 v68, 0x3fb8aa3b, v68
	v_mul_f32_e32 v69, 0x3fb8aa3b, v69
	v_lshlrev_b32_e32 v70, 16, v39
	v_and_b32_e32 v71, 0xffff0000, v39
	v_mul_f32_e32 v70, 0x3fb8aa3b, v70
	v_mul_f32_e32 v71, 0x3fb8aa3b, v71
	ds_write_b128 v153, v[64:67]
	ds_write_b128 v153, v[68:71] offset:128
	s_waitcnt lgkmcnt(0)
	ds_read_b32 v124, v154 offset:0
	ds_read_b32 v125, v154 offset:256
	ds_read_b32 v126, v154 offset:512
	ds_read_b32 v127, v154 offset:768
	ds_read_b32 v128, v154 offset:1024
	ds_read_b32 v129, v154 offset:1280
	ds_read_b32 v130, v154 offset:1536
	ds_read_b32 v131, v154 offset:1792
	v_lshlrev_b32_e32 v108, 16, v32
	v_and_b32_e32 v109, 0xffff0000, v32
	v_lshlrev_b32_e32 v110, 16, v40
	v_and_b32_e32 v111, 0xffff0000, v40
	v_lshlrev_b32_e32 v96, 16, v28
	v_and_b32_e32 v97, 0xffff0000, v28
	v_pk_add_f32 v[112:113], v[110:111], -1.0 op_sel_hi:[1,0]
	v_pk_mul_f32 v[114:115], v[12:13], v[108:109]
	v_pk_fma_f32 v[112:113], v[20:21], v[112:113], 1.0 op_sel_hi:[1,1,0]
	v_pk_mul_f32 v[88:89], v[44:45], v[114:115] op_sel_hi:[0,1]
	v_pk_mul_f32 v[72:73], v[112:113], v[108:109]
	v_pk_mul_f32 v[80:81], v[88:89], v[110:111]
	v_lshlrev_b32_e32 v108, 16, v33
	v_and_b32_e32 v109, 0xffff0000, v33
	v_lshlrev_b32_e32 v110, 16, v41
	v_and_b32_e32 v111, 0xffff0000, v41
	v_lshlrev_b32_e32 v98, 16, v29
	v_and_b32_e32 v99, 0xffff0000, v29
	v_pk_add_f32 v[112:113], v[110:111], -1.0 op_sel_hi:[1,0]
	v_pk_mul_f32 v[114:115], v[14:15], v[108:109]
	v_pk_fma_f32 v[112:113], v[22:23], v[112:113], 1.0 op_sel_hi:[1,1,0]
	v_pk_mul_f32 v[90:91], v[44:45], v[114:115] op_sel_hi:[0,1]
	v_pk_mul_f32 v[74:75], v[112:113], v[108:109]
	v_pk_mul_f32 v[82:83], v[90:91], v[110:111]
	v_lshlrev_b32_e32 v108, 16, v34
	v_and_b32_e32 v109, 0xffff0000, v34
	v_lshlrev_b32_e32 v110, 16, v42
	v_and_b32_e32 v111, 0xffff0000, v42
	v_lshlrev_b32_e32 v100, 16, v30
	v_and_b32_e32 v101, 0xffff0000, v30
	v_pk_add_f32 v[112:113], v[110:111], -1.0 op_sel_hi:[1,0]
	v_pk_mul_f32 v[114:115], v[16:17], v[108:109]
	v_pk_fma_f32 v[112:113], v[24:25], v[112:113], 1.0 op_sel_hi:[1,1,0]
	v_pk_mul_f32 v[92:93], v[44:45], v[114:115] op_sel_hi:[0,1]
	v_pk_mul_f32 v[76:77], v[112:113], v[108:109]
	v_pk_mul_f32 v[84:85], v[92:93], v[110:111]
	v_lshlrev_b32_e32 v108, 16, v35
	v_and_b32_e32 v109, 0xffff0000, v35
	v_lshlrev_b32_e32 v110, 16, v43
	v_and_b32_e32 v111, 0xffff0000, v43
	v_lshlrev_b32_e32 v102, 16, v31
	v_and_b32_e32 v103, 0xffff0000, v31
	v_pk_add_f32 v[112:113], v[110:111], -1.0 op_sel_hi:[1,0]
	v_pk_mul_f32 v[114:115], v[18:19], v[108:109]
	v_pk_fma_f32 v[112:113], v[26:27], v[112:113], 1.0 op_sel_hi:[1,1,0]
	v_pk_mul_f32 v[94:95], v[44:45], v[114:115] op_sel_hi:[0,1]
	v_pk_mul_f32 v[78:79], v[112:113], v[108:109]
	v_pk_mul_f32 v[86:87], v[94:95], v[110:111]
	v_lshlrev_b32_e32 v104, 16, v45
	v_and_b32_e32 v105, 0xffff0000, v45
	s_waitcnt lgkmcnt(0)
	v_add_f32_e32 v125, v124, v125
	v_add_f32_e32 v126, v125, v126
	v_add_f32_e32 v127, v126, v127
	v_add_f32_e32 v128, v127, v128
	v_add_f32_e32 v129, v128, v129
	v_add_f32_e32 v130, v129, v130
	v_add_f32_e32 v131, v130, v131
	v_exp_f32_e64 v124, -v124
	v_exp_f32_e64 v125, -v125
	v_exp_f32_e64 v126, -v126
	v_exp_f32_e64 v127, -v127
	v_exp_f32_e64 v128, -v128
	v_exp_f32_e64 v129, -v129
	v_exp_f32_e64 v130, -v130
	v_exp_f32_e64 v131, -v131
	s_nop 0
	ds_write_b32 v155, v124 offset:256
	ds_write_b32 v155, v125 offset:512
	ds_write_b32 v155, v126 offset:768
	ds_write_b32 v155, v127 offset:1024
	ds_write_b32 v155, v128 offset:1280
	ds_write_b32 v155, v129 offset:1536
	ds_write_b32 v155, v130 offset:1792
	ds_write_b32 v155, v131 offset:2048
	ds_write_b32 v159, v131 offset:0
	s_waitcnt lgkmcnt(0)
	ds_read_b128 v[64:67], v153 offset:2048
	ds_read_b128 v[68:71], v153 offset:2176
	ds_read_b128 v[116:119], v153 offset:2304
	ds_read_b128 v[120:123], v153 offset:2432
	s_waitcnt lgkmcnt(0)
	v_rcp_f32_e32 v124, v116
	v_rcp_f32_e32 v125, v117
	v_rcp_f32_e32 v126, v118
	v_rcp_f32_e32 v127, v119
	v_rcp_f32_e32 v128, v120
	v_rcp_f32_e32 v129, v121
	v_rcp_f32_e32 v130, v122
	v_rcp_f32_e32 v131, v123
	s_nop 1
	v_pk_mul_f32 v[72:73], v[72:73], v[124:125]
	v_pk_mul_f32 v[80:81], v[80:81], v[124:125]
	v_pk_mul_f32 v[88:89], v[88:89], v[64:65]
	v_pk_mul_f32 v[96:97], v[96:97], v[116:117]
	v_pk_mul_f32 v[74:75], v[74:75], v[126:127]
	v_pk_mul_f32 v[82:83], v[82:83], v[126:127]
	v_pk_mul_f32 v[90:91], v[90:91], v[66:67]
	v_pk_mul_f32 v[98:99], v[98:99], v[118:119]
	v_pk_mul_f32 v[76:77], v[76:77], v[128:129]
	v_pk_mul_f32 v[84:85], v[84:85], v[128:129]
	v_pk_mul_f32 v[92:93], v[92:93], v[68:69]
	v_pk_mul_f32 v[100:101], v[100:101], v[120:121]
	v_pk_mul_f32 v[78:79], v[78:79], v[130:131]
	v_pk_mul_f32 v[86:87], v[86:87], v[130:131]
	v_pk_mul_f32 v[94:95], v[94:95], v[70:71]
	v_pk_mul_f32 v[102:103], v[102:103], v[122:123]
	ds_write_b128 v8, v[72:75] offset:0
	ds_write_b128 v8, v[76:79] offset:128
	ds_write_b128 v8, v[80:83] offset:256
	ds_write_b128 v8, v[84:87] offset:384
	ds_write2_b32 v138, v96, v97 offset0:1 offset1:3
	ds_write2_b32 v139, v88, v89 offset0:0 offset1:2
	ds_write2_b32 v138, v98, v99 offset0:65 offset1:67
	ds_write2_b32 v139, v90, v91 offset0:64 offset1:66
	ds_write2_b32 v138, v100, v101 offset0:33 offset1:35
	ds_write2_b32 v139, v92, v93 offset0:32 offset1:34
	ds_write2_b32 v138, v102, v103 offset0:97 offset1:99
	ds_write2_b32 v139, v94, v95 offset0:96 offset1:98
	ds_write2_b32 v142, v104, v105 offset1:36
	s_and_saveexec_b64 s[68:69], s[12:13]
	ds_write_b128 v158, v[88:91] offset:0
	ds_write_b128 v158, v[92:95] offset:128
	s_mov_b64 exec, s[68:69]
	global_load_dwordx2 v[28:29], v5, s[36:37]
	global_load_dwordx2 v[30:31], v5, s[36:37] offset:64
	global_load_dwordx2 v[32:33], v5, s[38:39]
	global_load_dwordx2 v[34:35], v5, s[38:39] offset:64
	global_load_dwordx2 v[36:37], v5, s[40:41]
	global_load_dwordx2 v[38:39], v5, s[40:41] offset:64
	global_load_dwordx2 v[40:41], v5, s[42:43]
	global_load_dwordx2 v[42:43], v5, s[42:43] offset:64
	global_load_dword v44, v6, s[46:47]
	global_load_dword v45, v9, s[44:45]
	v_add_u32_e32 v5, s54, v5
	v_add_u32_e32 v6, s55, v6
	v_add_u32_e32 v9, s54, v9
	ds_read_b128 v[120:123], v11 offset:0
	ds_read_b128 v[124:127], v11 offset:16
	ds_read_b128 v[128:131], v11 offset:32
	ds_read_b128 v[132:135], v11 offset:48
	s_waitcnt lgkmcnt(0)
	v_pk_add_f32 v[120:121], v[120:121], v[122:123]
	v_pk_add_f32 v[124:125], v[124:125], v[126:127]
	v_pk_add_f32 v[120:121], v[120:121], v[124:125]
	v_add_f32_e32 v136, v120, v121
	v_pk_add_f32 v[128:129], v[128:129], v[130:131]
	v_pk_add_f32 v[132:133], v[132:133], v[134:135]
	v_pk_add_f32 v[128:129], v[128:129], v[132:133]
	v_add_f32_e32 v137, v128, v129
	global_store_dwordx2 v7, v[136:137], s[48:49]
	v_add_u32_e32 v7, s64, v7
	s_add_i32 s6, s6, 1
	v_add_u32_e32 v146, 1, v146
	s_waitcnt lgkmcnt(0)
	ds_write_b32 v145, v146
	s_sub_u32 s65, s6, 1
	ds_read_b128 v[148:151], v144
	s_waitcnt lgkmcnt(0)
	v_min_u32_e32 v148, v148, v149
	v_min3_u32 v148, v148, v150, v151
	s_nop 1
	v_readfirstlane_b32 s68, v148
	s_cmp_ge_u32 s68, s65
	s_cbranch_scc1 .Lsc_G_gom1
	s_mov_b32 s69, 0x100000

.Lsc_G_gom1:
	s_waitcnt vmcnt(10)
	v_lshlrev_b32_e32 v64, 16, v54
	v_and_b32_e32 v65, 0xffff0000, v54
	v_mul_f32_e32 v64, 0x3fb8aa3b, v64
	v_mul_f32_e32 v65, 0x3fb8aa3b, v65
	v_lshlrev_b32_e32 v66, 16, v55
	v_and_b32_e32 v67, 0xffff0000, v55
	v_mul_f32_e32 v66, 0x3fb8aa3b, v66
	v_mul_f32_e32 v67, 0x3fb8aa3b, v67
	v_lshlrev_b32_e32 v68, 16, v56
	v_and_b32_e32 v69, 0xffff0000, v56
	v_mul_f32_e32 v68, 0x3fb8aa3b, v68
	v_mul_f32_e32 v69, 0x3fb8aa3b, v69
	v_lshlrev_b32_e32 v70, 16, v57
	v_and_b32_e32 v71, 0xffff0000, v57
	v_mul_f32_e32 v70, 0x3fb8aa3b, v70
	v_mul_f32_e32 v71, 0x3fb8aa3b, v71
	ds_write_b128 v153, v[64:67]
	ds_write_b128 v153, v[68:71] offset:128
	s_waitcnt lgkmcnt(0)
	ds_read_b32 v124, v154 offset:0
	ds_read_b32 v125, v154 offset:256
	ds_read_b32 v126, v154 offset:512
	ds_read_b32 v127, v154 offset:768
	ds_read_b32 v128, v154 offset:1024
	ds_read_b32 v129, v154 offset:1280
	ds_read_b32 v130, v154 offset:1536
	ds_read_b32 v131, v154 offset:1792
	v_lshlrev_b32_e32 v108, 16, v50
	v_and_b32_e32 v109, 0xffff0000, v50
	v_lshlrev_b32_e32 v110, 16, v58
	v_and_b32_e32 v111, 0xffff0000, v58
	v_lshlrev_b32_e32 v96, 16, v46
	v_and_b32_e32 v97, 0xffff0000, v46
	v_pk_add_f32 v[112:113], v[110:111], -1.0 op_sel_hi:[1,0]
	v_pk_mul_f32 v[114:115], v[12:13], v[108:109]
	v_pk_fma_f32 v[112:113], v[20:21], v[112:113], 1.0 op_sel_hi:[1,1,0]
	v_pk_mul_f32 v[88:89], v[62:63], v[114:115] op_sel_hi:[0,1]
	v_pk_mul_f32 v[72:73], v[112:113], v[108:109]
	v_pk_mul_f32 v[80:81], v[88:89], v[110:111]
	v_lshlrev_b32_e32 v108, 16, v51
	v_and_b32_e32 v109, 0xffff0000, v51
	v_lshlrev_b32_e32 v110, 16, v59
	v_and_b32_e32 v111, 0xffff0000, v59
	v_lshlrev_b32_e32 v98, 16, v47
	v_and_b32_e32 v99, 0xffff0000, v47
	v_pk_add_f32 v[112:113], v[110:111], -1.0 op_sel_hi:[1,0]
	v_pk_mul_f32 v[114:115], v[14:15], v[108:109]
	v_pk_fma_f32 v[112:113], v[22:23], v[112:113], 1.0 op_sel_hi:[1,1,0]
	v_pk_mul_f32 v[90:91], v[62:63], v[114:115] op_sel_hi:[0,1]
	v_pk_mul_f32 v[74:75], v[112:113], v[108:109]
	v_pk_mul_f32 v[82:83], v[90:91], v[110:111]
	v_lshlrev_b32_e32 v108, 16, v52
	v_and_b32_e32 v109, 0xffff0000, v52
	v_lshlrev_b32_e32 v110, 16, v60
	v_and_b32_e32 v111, 0xffff0000, v60
	v_lshlrev_b32_e32 v100, 16, v48
	v_and_b32_e32 v101, 0xffff0000, v48
	v_pk_add_f32 v[112:113], v[110:111], -1.0 op_sel_hi:[1,0]
	v_pk_mul_f32 v[114:115], v[16:17], v[108:109]
	v_pk_fma_f32 v[112:113], v[24:25], v[112:113], 1.0 op_sel_hi:[1,1,0]
	v_pk_mul_f32 v[92:93], v[62:63], v[114:115] op_sel_hi:[0,1]
	v_pk_mul_f32 v[76:77], v[112:113], v[108:109]
	v_pk_mul_f32 v[84:85], v[92:93], v[110:111]
	v_lshlrev_b32_e32 v108, 16, v53
	v_and_b32_e32 v109, 0xffff0000, v53
	v_lshlrev_b32_e32 v110, 16, v61
	v_and_b32_e32 v111, 0xffff0000, v61
	v_lshlrev_b32_e32 v102, 16, v49
	v_and_b32_e32 v103, 0xffff0000, v49
	v_pk_add_f32 v[112:113], v[110:111], -1.0 op_sel_hi:[1,0]
	v_pk_mul_f32 v[114:115], v[18:19], v[108:109]
	v_pk_fma_f32 v[112:113], v[26:27], v[112:113], 1.0 op_sel_hi:[1,1,0]
	v_pk_mul_f32 v[94:95], v[62:63], v[114:115] op_sel_hi:[0,1]
	v_pk_mul_f32 v[78:79], v[112:113], v[108:109]
	v_pk_mul_f32 v[86:87], v[94:95], v[110:111]
	v_lshlrev_b32_e32 v104, 16, v63
	v_and_b32_e32 v105, 0xffff0000, v63
	s_waitcnt lgkmcnt(0)
	v_add_f32_e32 v125, v124, v125
	v_add_f32_e32 v126, v125, v126
	v_add_f32_e32 v127, v126, v127
	v_add_f32_e32 v128, v127, v128
	v_add_f32_e32 v129, v128, v129
	v_add_f32_e32 v130, v129, v130
	v_add_f32_e32 v131, v130, v131
	v_exp_f32_e64 v124, -v124
	v_exp_f32_e64 v125, -v125
	v_exp_f32_e64 v126, -v126
	v_exp_f32_e64 v127, -v127
	v_exp_f32_e64 v128, -v128
	v_exp_f32_e64 v129, -v129
	v_exp_f32_e64 v130, -v130
	v_exp_f32_e64 v131, -v131
	s_nop 0
	ds_write_b32 v155, v124 offset:256
	ds_write_b32 v155, v125 offset:512
	ds_write_b32 v155, v126 offset:768
	ds_write_b32 v155, v127 offset:1024
	ds_write_b32 v155, v128 offset:1280
	ds_write_b32 v155, v129 offset:1536
	ds_write_b32 v155, v130 offset:1792
	ds_write_b32 v155, v131 offset:2048
	ds_write_b32 v159, v131 offset:34816
	s_waitcnt lgkmcnt(0)
	ds_read_b128 v[64:67], v153 offset:2048
	ds_read_b128 v[68:71], v153 offset:2176
	ds_read_b128 v[116:119], v153 offset:2304
	ds_read_b128 v[120:123], v153 offset:2432
	s_waitcnt lgkmcnt(0)
	v_rcp_f32_e32 v124, v116
	v_rcp_f32_e32 v125, v117
	v_rcp_f32_e32 v126, v118
	v_rcp_f32_e32 v127, v119
	v_rcp_f32_e32 v128, v120
	v_rcp_f32_e32 v129, v121
	v_rcp_f32_e32 v130, v122
	v_rcp_f32_e32 v131, v123
	s_nop 1
	v_pk_mul_f32 v[72:73], v[72:73], v[124:125]
	v_pk_mul_f32 v[80:81], v[80:81], v[124:125]
	v_pk_mul_f32 v[88:89], v[88:89], v[64:65]
	v_pk_mul_f32 v[96:97], v[96:97], v[116:117]
	v_pk_mul_f32 v[74:75], v[74:75], v[126:127]
	v_pk_mul_f32 v[82:83], v[82:83], v[126:127]
	v_pk_mul_f32 v[90:91], v[90:91], v[66:67]
	v_pk_mul_f32 v[98:99], v[98:99], v[118:119]
	v_pk_mul_f32 v[76:77], v[76:77], v[128:129]
	v_pk_mul_f32 v[84:85], v[84:85], v[128:129]
	v_pk_mul_f32 v[92:93], v[92:93], v[68:69]
	v_pk_mul_f32 v[100:101], v[100:101], v[120:121]
	v_pk_mul_f32 v[78:79], v[78:79], v[130:131]
	v_pk_mul_f32 v[86:87], v[86:87], v[130:131]
	v_pk_mul_f32 v[94:95], v[94:95], v[70:71]
	v_pk_mul_f32 v[102:103], v[102:103], v[122:123]
	ds_write_b128 v8, v[72:75] offset:34816
	ds_write_b128 v8, v[76:79] offset:34944
	ds_write_b128 v8, v[80:83] offset:35072
	ds_write_b128 v8, v[84:87] offset:35200
	ds_write2_b32 v140, v96, v97 offset0:1 offset1:3
	ds_write2_b32 v141, v88, v89 offset0:0 offset1:2
	ds_write2_b32 v140, v98, v99 offset0:65 offset1:67
	ds_write2_b32 v141, v90, v91 offset0:64 offset1:66
	ds_write2_b32 v140, v100, v101 offset0:33 offset1:35
	ds_write2_b32 v141, v92, v93 offset0:32 offset1:34
	ds_write2_b32 v140, v102, v103 offset0:97 offset1:99
	ds_write2_b32 v141, v94, v95 offset0:96 offset1:98
	ds_write2_b32 v143, v104, v105 offset1:36
	s_and_saveexec_b64 s[68:69], s[12:13]
	ds_write_b128 v158, v[88:91] offset:34816
	ds_write_b128 v158, v[92:95] offset:34944
	s_mov_b64 exec, s[68:69]
	global_load_dwordx2 v[46:47], v5, s[36:37]
	global_load_dwordx2 v[48:49], v5, s[36:37] offset:64
	global_load_dwordx2 v[50:51], v5, s[38:39]
	global_load_dwordx2 v[52:53], v5, s[38:39] offset:64
	global_load_dwordx2 v[54:55], v5, s[40:41]
	global_load_dwordx2 v[56:57], v5, s[40:41] offset:64
	global_load_dwordx2 v[58:59], v5, s[42:43]
	global_load_dwordx2 v[60:61], v5, s[42:43] offset:64
	global_load_dword v62, v6, s[46:47]
	global_load_dword v63, v9, s[44:45]
	v_add_u32_e32 v5, s54, v5
	v_add_u32_e32 v6, s55, v6
	v_add_u32_e32 v9, s54, v9
	ds_read_b128 v[120:123], v11 offset:16384
	ds_read_b128 v[124:127], v11 offset:16400
	ds_read_b128 v[128:131], v11 offset:16416
	ds_read_b128 v[132:135], v11 offset:16432
	s_waitcnt lgkmcnt(0)
	v_pk_add_f32 v[120:121], v[120:121], v[122:123]
	v_pk_add_f32 v[124:125], v[124:125], v[126:127]
	v_pk_add_f32 v[120:121], v[120:121], v[124:125]
	v_add_f32_e32 v136, v120, v121
	v_pk_add_f32 v[128:129], v[128:129], v[130:131]
	v_pk_add_f32 v[132:133], v[132:133], v[134:135]
	v_pk_add_f32 v[128:129], v[128:129], v[132:133]
	v_add_f32_e32 v137, v128, v129
	global_store_dwordx2 v7, v[136:137], s[48:49]
	v_add_u32_e32 v7, s64, v7
	s_add_i32 s6, s6, 1
	v_add_u32_e32 v146, 1, v146
	s_waitcnt lgkmcnt(0)
	ds_write_b32 v145, v146
	s_cmp_lt_u32 s6, 0xfe
	s_cbranch_scc1 .Lsc_G_loop
	s_sub_u32 s65, s6, 1
	ds_read_b128 v[148:151], v144
	s_waitcnt lgkmcnt(0)
	v_min_u32_e32 v148, v148, v149
	v_min3_u32 v148, v148, v150, v151
	s_nop 1
	v_readfirstlane_b32 s68, v148
	s_cmp_ge_u32 s68, s65
	s_cbranch_scc1 .Lsc_G_goz0
	s_mov_b32 s69, 0x100000

.Lsc_G_goz0:
	s_waitcnt vmcnt(10)
	v_lshlrev_b32_e32 v64, 16, v36
	v_and_b32_e32 v65, 0xffff0000, v36
	v_mul_f32_e32 v64, 0x3fb8aa3b, v64
	v_mul_f32_e32 v65, 0x3fb8aa3b, v65
	v_lshlrev_b32_e32 v66, 16, v37
	v_and_b32_e32 v67, 0xffff0000, v37
	v_mul_f32_e32 v66, 0x3fb8aa3b, v66
	v_mul_f32_e32 v67, 0x3fb8aa3b, v67
	v_lshlrev_b32_e32 v68, 16, v38
	v_and_b32_e32 v69, 0xffff0000, v38
	v_mul_f32_e32 v68, 0x3fb8aa3b, v68
	v_mul_f32_e32 v69, 0x3fb8aa3b, v69
	v_lshlrev_b32_e32 v70, 16, v39
	v_and_b32_e32 v71, 0xffff0000, v39
	v_mul_f32_e32 v70, 0x3fb8aa3b, v70
	v_mul_f32_e32 v71, 0x3fb8aa3b, v71
	ds_write_b128 v153, v[64:67]
	ds_write_b128 v153, v[68:71] offset:128
	s_waitcnt lgkmcnt(0)
	ds_read_b32 v124, v154 offset:0
	ds_read_b32 v125, v154 offset:256
	ds_read_b32 v126, v154 offset:512
	ds_read_b32 v127, v154 offset:768
	ds_read_b32 v128, v154 offset:1024
	ds_read_b32 v129, v154 offset:1280
	ds_read_b32 v130, v154 offset:1536
	ds_read_b32 v131, v154 offset:1792
	v_lshlrev_b32_e32 v108, 16, v32
	v_and_b32_e32 v109, 0xffff0000, v32
	v_lshlrev_b32_e32 v110, 16, v40
	v_and_b32_e32 v111, 0xffff0000, v40
	v_lshlrev_b32_e32 v96, 16, v28
	v_and_b32_e32 v97, 0xffff0000, v28
	v_pk_add_f32 v[112:113], v[110:111], -1.0 op_sel_hi:[1,0]
	v_pk_mul_f32 v[114:115], v[12:13], v[108:109]
	v_pk_fma_f32 v[112:113], v[20:21], v[112:113], 1.0 op_sel_hi:[1,1,0]
	v_pk_mul_f32 v[88:89], v[44:45], v[114:115] op_sel_hi:[0,1]
	v_pk_mul_f32 v[72:73], v[112:113], v[108:109]
	v_pk_mul_f32 v[80:81], v[88:89], v[110:111]
	v_lshlrev_b32_e32 v108, 16, v33
	v_and_b32_e32 v109, 0xffff0000, v33
	v_lshlrev_b32_e32 v110, 16, v41
	v_and_b32_e32 v111, 0xffff0000, v41
	v_lshlrev_b32_e32 v98, 16, v29
	v_and_b32_e32 v99, 0xffff0000, v29
	v_pk_add_f32 v[112:113], v[110:111], -1.0 op_sel_hi:[1,0]
	v_pk_mul_f32 v[114:115], v[14:15], v[108:109]
	v_pk_fma_f32 v[112:113], v[22:23], v[112:113], 1.0 op_sel_hi:[1,1,0]
	v_pk_mul_f32 v[90:91], v[44:45], v[114:115] op_sel_hi:[0,1]
	v_pk_mul_f32 v[74:75], v[112:113], v[108:109]
	v_pk_mul_f32 v[82:83], v[90:91], v[110:111]
	v_lshlrev_b32_e32 v108, 16, v34
	v_and_b32_e32 v109, 0xffff0000, v34
	v_lshlrev_b32_e32 v110, 16, v42
	v_and_b32_e32 v111, 0xffff0000, v42
	v_lshlrev_b32_e32 v100, 16, v30
	v_and_b32_e32 v101, 0xffff0000, v30
	v_pk_add_f32 v[112:113], v[110:111], -1.0 op_sel_hi:[1,0]
	v_pk_mul_f32 v[114:115], v[16:17], v[108:109]
	v_pk_fma_f32 v[112:113], v[24:25], v[112:113], 1.0 op_sel_hi:[1,1,0]
	v_pk_mul_f32 v[92:93], v[44:45], v[114:115] op_sel_hi:[0,1]
	v_pk_mul_f32 v[76:77], v[112:113], v[108:109]
	v_pk_mul_f32 v[84:85], v[92:93], v[110:111]
	v_lshlrev_b32_e32 v108, 16, v35
	v_and_b32_e32 v109, 0xffff0000, v35
	v_lshlrev_b32_e32 v110, 16, v43
	v_and_b32_e32 v111, 0xffff0000, v43
	v_lshlrev_b32_e32 v102, 16, v31
	v_and_b32_e32 v103, 0xffff0000, v31
	v_pk_add_f32 v[112:113], v[110:111], -1.0 op_sel_hi:[1,0]
	v_pk_mul_f32 v[114:115], v[18:19], v[108:109]
	v_pk_fma_f32 v[112:113], v[26:27], v[112:113], 1.0 op_sel_hi:[1,1,0]
	v_pk_mul_f32 v[94:95], v[44:45], v[114:115] op_sel_hi:[0,1]
	v_pk_mul_f32 v[78:79], v[112:113], v[108:109]
	v_pk_mul_f32 v[86:87], v[94:95], v[110:111]
	v_lshlrev_b32_e32 v104, 16, v45
	v_and_b32_e32 v105, 0xffff0000, v45
	s_waitcnt lgkmcnt(0)
	v_add_f32_e32 v125, v124, v125
	v_add_f32_e32 v126, v125, v126
	v_add_f32_e32 v127, v126, v127
	v_add_f32_e32 v128, v127, v128
	v_add_f32_e32 v129, v128, v129
	v_add_f32_e32 v130, v129, v130
	v_add_f32_e32 v131, v130, v131
	v_exp_f32_e64 v124, -v124
	v_exp_f32_e64 v125, -v125
	v_exp_f32_e64 v126, -v126
	v_exp_f32_e64 v127, -v127
	v_exp_f32_e64 v128, -v128
	v_exp_f32_e64 v129, -v129
	v_exp_f32_e64 v130, -v130
	v_exp_f32_e64 v131, -v131
	s_nop 0
	ds_write_b32 v155, v124 offset:256
	ds_write_b32 v155, v125 offset:512
	ds_write_b32 v155, v126 offset:768
	ds_write_b32 v155, v127 offset:1024
	ds_write_b32 v155, v128 offset:1280
	ds_write_b32 v155, v129 offset:1536
	ds_write_b32 v155, v130 offset:1792
	ds_write_b32 v155, v131 offset:2048
	ds_write_b32 v159, v131 offset:0
	s_waitcnt lgkmcnt(0)
	ds_read_b128 v[64:67], v153 offset:2048
	ds_read_b128 v[68:71], v153 offset:2176
	ds_read_b128 v[116:119], v153 offset:2304
	ds_read_b128 v[120:123], v153 offset:2432
	s_waitcnt lgkmcnt(0)
	v_rcp_f32_e32 v124, v116
	v_rcp_f32_e32 v125, v117
	v_rcp_f32_e32 v126, v118
	v_rcp_f32_e32 v127, v119
	v_rcp_f32_e32 v128, v120
	v_rcp_f32_e32 v129, v121
	v_rcp_f32_e32 v130, v122
	v_rcp_f32_e32 v131, v123
	s_nop 1
	v_pk_mul_f32 v[72:73], v[72:73], v[124:125]
	v_pk_mul_f32 v[80:81], v[80:81], v[124:125]
	v_pk_mul_f32 v[88:89], v[88:89], v[64:65]
	v_pk_mul_f32 v[96:97], v[96:97], v[116:117]
	v_pk_mul_f32 v[74:75], v[74:75], v[126:127]
	v_pk_mul_f32 v[82:83], v[82:83], v[126:127]
	v_pk_mul_f32 v[90:91], v[90:91], v[66:67]
	v_pk_mul_f32 v[98:99], v[98:99], v[118:119]
	v_pk_mul_f32 v[76:77], v[76:77], v[128:129]
	v_pk_mul_f32 v[84:85], v[84:85], v[128:129]
	v_pk_mul_f32 v[92:93], v[92:93], v[68:69]
	v_pk_mul_f32 v[100:101], v[100:101], v[120:121]
	v_pk_mul_f32 v[78:79], v[78:79], v[130:131]
	v_pk_mul_f32 v[86:87], v[86:87], v[130:131]
	v_pk_mul_f32 v[94:95], v[94:95], v[70:71]
	v_pk_mul_f32 v[102:103], v[102:103], v[122:123]
	ds_write_b128 v8, v[72:75] offset:0
	ds_write_b128 v8, v[76:79] offset:128
	ds_write_b128 v8, v[80:83] offset:256
	ds_write_b128 v8, v[84:87] offset:384
	ds_write2_b32 v138, v96, v97 offset0:1 offset1:3
	ds_write2_b32 v139, v88, v89 offset0:0 offset1:2
	ds_write2_b32 v138, v98, v99 offset0:65 offset1:67
	ds_write2_b32 v139, v90, v91 offset0:64 offset1:66
	ds_write2_b32 v138, v100, v101 offset0:33 offset1:35
	ds_write2_b32 v139, v92, v93 offset0:32 offset1:34
	ds_write2_b32 v138, v102, v103 offset0:97 offset1:99
	ds_write2_b32 v139, v94, v95 offset0:96 offset1:98
	ds_write2_b32 v142, v104, v105 offset1:36
	s_and_saveexec_b64 s[68:69], s[12:13]
	ds_write_b128 v158, v[88:91] offset:0
	ds_write_b128 v158, v[92:95] offset:128
	s_mov_b64 exec, s[68:69]
	ds_read_b128 v[120:123], v11 offset:0
	ds_read_b128 v[124:127], v11 offset:16
	ds_read_b128 v[128:131], v11 offset:32
	ds_read_b128 v[132:135], v11 offset:48
	s_waitcnt lgkmcnt(0)
	v_pk_add_f32 v[120:121], v[120:121], v[122:123]
	v_pk_add_f32 v[124:125], v[124:125], v[126:127]
	v_pk_add_f32 v[120:121], v[120:121], v[124:125]
	v_add_f32_e32 v136, v120, v121
	v_pk_add_f32 v[128:129], v[128:129], v[130:131]
	v_pk_add_f32 v[132:133], v[132:133], v[134:135]
	v_pk_add_f32 v[128:129], v[128:129], v[132:133]
	v_add_f32_e32 v137, v128, v129
	global_store_dwordx2 v7, v[136:137], s[48:49]
	v_add_u32_e32 v7, s64, v7
	s_add_i32 s6, s6, 1
	v_add_u32_e32 v146, 1, v146
	s_waitcnt lgkmcnt(0)
	ds_write_b32 v145, v146
	s_sub_u32 s65, s6, 1
	ds_read_b128 v[148:151], v144
	s_waitcnt lgkmcnt(0)
	v_min_u32_e32 v148, v148, v149
	v_min3_u32 v148, v148, v150, v151
	s_nop 1
	v_readfirstlane_b32 s68, v148
	s_cmp_ge_u32 s68, s65
	s_cbranch_scc1 .Lsc_G_goz1
	s_mov_b32 s69, 0x100000

.Lsc_G_goz1:
	s_waitcnt vmcnt(0)
	v_lshlrev_b32_e32 v64, 16, v54
	v_and_b32_e32 v65, 0xffff0000, v54
	v_mul_f32_e32 v64, 0x3fb8aa3b, v64
	v_mul_f32_e32 v65, 0x3fb8aa3b, v65
	v_lshlrev_b32_e32 v66, 16, v55
	v_and_b32_e32 v67, 0xffff0000, v55
	v_mul_f32_e32 v66, 0x3fb8aa3b, v66
	v_mul_f32_e32 v67, 0x3fb8aa3b, v67
	v_lshlrev_b32_e32 v68, 16, v56
	v_and_b32_e32 v69, 0xffff0000, v56
	v_mul_f32_e32 v68, 0x3fb8aa3b, v68
	v_mul_f32_e32 v69, 0x3fb8aa3b, v69
	v_lshlrev_b32_e32 v70, 16, v57
	v_and_b32_e32 v71, 0xffff0000, v57
	v_mul_f32_e32 v70, 0x3fb8aa3b, v70
	v_mul_f32_e32 v71, 0x3fb8aa3b, v71
	ds_write_b128 v153, v[64:67]
	ds_write_b128 v153, v[68:71] offset:128
	s_waitcnt lgkmcnt(0)
	ds_read_b32 v124, v154 offset:0
	ds_read_b32 v125, v154 offset:256
	ds_read_b32 v126, v154 offset:512
	ds_read_b32 v127, v154 offset:768
	ds_read_b32 v128, v154 offset:1024
	ds_read_b32 v129, v154 offset:1280
	ds_read_b32 v130, v154 offset:1536
	ds_read_b32 v131, v154 offset:1792
	v_lshlrev_b32_e32 v108, 16, v50
	v_and_b32_e32 v109, 0xffff0000, v50
	v_lshlrev_b32_e32 v110, 16, v58
	v_and_b32_e32 v111, 0xffff0000, v58
	v_lshlrev_b32_e32 v96, 16, v46
	v_and_b32_e32 v97, 0xffff0000, v46
	v_pk_add_f32 v[112:113], v[110:111], -1.0 op_sel_hi:[1,0]
	v_pk_mul_f32 v[114:115], v[12:13], v[108:109]
	v_pk_fma_f32 v[112:113], v[20:21], v[112:113], 1.0 op_sel_hi:[1,1,0]
	v_pk_mul_f32 v[88:89], v[62:63], v[114:115] op_sel_hi:[0,1]
	v_pk_mul_f32 v[72:73], v[112:113], v[108:109]
	v_pk_mul_f32 v[80:81], v[88:89], v[110:111]
	v_lshlrev_b32_e32 v108, 16, v51
	v_and_b32_e32 v109, 0xffff0000, v51
	v_lshlrev_b32_e32 v110, 16, v59
	v_and_b32_e32 v111, 0xffff0000, v59
	v_lshlrev_b32_e32 v98, 16, v47
	v_and_b32_e32 v99, 0xffff0000, v47
	v_pk_add_f32 v[112:113], v[110:111], -1.0 op_sel_hi:[1,0]
	v_pk_mul_f32 v[114:115], v[14:15], v[108:109]
	v_pk_fma_f32 v[112:113], v[22:23], v[112:113], 1.0 op_sel_hi:[1,1,0]
	v_pk_mul_f32 v[90:91], v[62:63], v[114:115] op_sel_hi:[0,1]
	v_pk_mul_f32 v[74:75], v[112:113], v[108:109]
	v_pk_mul_f32 v[82:83], v[90:91], v[110:111]
	v_lshlrev_b32_e32 v108, 16, v52
	v_and_b32_e32 v109, 0xffff0000, v52
	v_lshlrev_b32_e32 v110, 16, v60
	v_and_b32_e32 v111, 0xffff0000, v60
	v_lshlrev_b32_e32 v100, 16, v48
	v_and_b32_e32 v101, 0xffff0000, v48
	v_pk_add_f32 v[112:113], v[110:111], -1.0 op_sel_hi:[1,0]
	v_pk_mul_f32 v[114:115], v[16:17], v[108:109]
	v_pk_fma_f32 v[112:113], v[24:25], v[112:113], 1.0 op_sel_hi:[1,1,0]
	v_pk_mul_f32 v[92:93], v[62:63], v[114:115] op_sel_hi:[0,1]
	v_pk_mul_f32 v[76:77], v[112:113], v[108:109]
	v_pk_mul_f32 v[84:85], v[92:93], v[110:111]
	v_lshlrev_b32_e32 v108, 16, v53
	v_and_b32_e32 v109, 0xffff0000, v53
	v_lshlrev_b32_e32 v110, 16, v61
	v_and_b32_e32 v111, 0xffff0000, v61
	v_lshlrev_b32_e32 v102, 16, v49
	v_and_b32_e32 v103, 0xffff0000, v49
	v_pk_add_f32 v[112:113], v[110:111], -1.0 op_sel_hi:[1,0]
	v_pk_mul_f32 v[114:115], v[18:19], v[108:109]
	v_pk_fma_f32 v[112:113], v[26:27], v[112:113], 1.0 op_sel_hi:[1,1,0]
	v_pk_mul_f32 v[94:95], v[62:63], v[114:115] op_sel_hi:[0,1]
	v_pk_mul_f32 v[78:79], v[112:113], v[108:109]
	v_pk_mul_f32 v[86:87], v[94:95], v[110:111]
	v_lshlrev_b32_e32 v104, 16, v63
	v_and_b32_e32 v105, 0xffff0000, v63
	s_waitcnt lgkmcnt(0)
	v_add_f32_e32 v125, v124, v125
	v_add_f32_e32 v126, v125, v126
	v_add_f32_e32 v127, v126, v127
	v_add_f32_e32 v128, v127, v128
	v_add_f32_e32 v129, v128, v129
	v_add_f32_e32 v130, v129, v130
	v_add_f32_e32 v131, v130, v131
	v_exp_f32_e64 v124, -v124
	v_exp_f32_e64 v125, -v125
	v_exp_f32_e64 v126, -v126
	v_exp_f32_e64 v127, -v127
	v_exp_f32_e64 v128, -v128
	v_exp_f32_e64 v129, -v129
	v_exp_f32_e64 v130, -v130
	v_exp_f32_e64 v131, -v131
	s_nop 0
	ds_write_b32 v155, v124 offset:256
	ds_write_b32 v155, v125 offset:512
	ds_write_b32 v155, v126 offset:768
	ds_write_b32 v155, v127 offset:1024
	ds_write_b32 v155, v128 offset:1280
	ds_write_b32 v155, v129 offset:1536
	ds_write_b32 v155, v130 offset:1792
	ds_write_b32 v155, v131 offset:2048
	ds_write_b32 v159, v131 offset:34816
	s_waitcnt lgkmcnt(0)
	ds_read_b128 v[64:67], v153 offset:2048
	ds_read_b128 v[68:71], v153 offset:2176
	ds_read_b128 v[116:119], v153 offset:2304
	ds_read_b128 v[120:123], v153 offset:2432
	s_waitcnt lgkmcnt(0)
	v_rcp_f32_e32 v124, v116
	v_rcp_f32_e32 v125, v117
	v_rcp_f32_e32 v126, v118
	v_rcp_f32_e32 v127, v119
	v_rcp_f32_e32 v128, v120
	v_rcp_f32_e32 v129, v121
	v_rcp_f32_e32 v130, v122
	v_rcp_f32_e32 v131, v123
	s_nop 1
	v_pk_mul_f32 v[72:73], v[72:73], v[124:125]
	v_pk_mul_f32 v[80:81], v[80:81], v[124:125]
	v_pk_mul_f32 v[88:89], v[88:89], v[64:65]
	v_pk_mul_f32 v[96:97], v[96:97], v[116:117]
	v_pk_mul_f32 v[74:75], v[74:75], v[126:127]
	v_pk_mul_f32 v[82:83], v[82:83], v[126:127]
	v_pk_mul_f32 v[90:91], v[90:91], v[66:67]
	v_pk_mul_f32 v[98:99], v[98:99], v[118:119]
	v_pk_mul_f32 v[76:77], v[76:77], v[128:129]
	v_pk_mul_f32 v[84:85], v[84:85], v[128:129]
	v_pk_mul_f32 v[92:93], v[92:93], v[68:69]
	v_pk_mul_f32 v[100:101], v[100:101], v[120:121]
	v_pk_mul_f32 v[78:79], v[78:79], v[130:131]
	v_pk_mul_f32 v[86:87], v[86:87], v[130:131]
	v_pk_mul_f32 v[94:95], v[94:95], v[70:71]
	v_pk_mul_f32 v[102:103], v[102:103], v[122:123]
	ds_write_b128 v8, v[72:75] offset:34816
	ds_write_b128 v8, v[76:79] offset:34944
	ds_write_b128 v8, v[80:83] offset:35072
	ds_write_b128 v8, v[84:87] offset:35200
	ds_write2_b32 v140, v96, v97 offset0:1 offset1:3
	ds_write2_b32 v141, v88, v89 offset0:0 offset1:2
	ds_write2_b32 v140, v98, v99 offset0:65 offset1:67
	ds_write2_b32 v141, v90, v91 offset0:64 offset1:66
	ds_write2_b32 v140, v100, v101 offset0:33 offset1:35
	ds_write2_b32 v141, v92, v93 offset0:32 offset1:34
	ds_write2_b32 v140, v102, v103 offset0:97 offset1:99
	ds_write2_b32 v141, v94, v95 offset0:96 offset1:98
	ds_write2_b32 v143, v104, v105 offset1:36
	s_and_saveexec_b64 s[68:69], s[12:13]
	ds_write_b128 v158, v[88:91] offset:34816
	ds_write_b128 v158, v[92:95] offset:34944
	s_mov_b64 exec, s[68:69]
	ds_read_b128 v[120:123], v11 offset:16384
	ds_read_b128 v[124:127], v11 offset:16400
	ds_read_b128 v[128:131], v11 offset:16416
	ds_read_b128 v[132:135], v11 offset:16432
	s_waitcnt lgkmcnt(0)
	v_pk_add_f32 v[120:121], v[120:121], v[122:123]
	v_pk_add_f32 v[124:125], v[124:125], v[126:127]
	v_pk_add_f32 v[120:121], v[120:121], v[124:125]
	v_add_f32_e32 v136, v120, v121
	v_pk_add_f32 v[128:129], v[128:129], v[130:131]
	v_pk_add_f32 v[132:133], v[132:133], v[134:135]
	v_pk_add_f32 v[128:129], v[128:129], v[132:133]
	v_add_f32_e32 v137, v128, v129
	global_store_dwordx2 v7, v[136:137], s[48:49]
	v_add_u32_e32 v7, s64, v7
	s_add_i32 s6, s6, 1
	v_add_u32_e32 v146, 1, v146
	s_waitcnt lgkmcnt(0)
	ds_write_b32 v145, v146
	s_sub_u32 s65, s6, 1
	ds_read_b128 v[148:151], v144
	s_waitcnt lgkmcnt(0)
	v_min_u32_e32 v148, v148, v149
	v_min3_u32 v148, v148, v150, v151
	s_nop 1
	v_readfirstlane_b32 s68, v148
	s_cmp_ge_u32 s68, s65
	s_cbranch_scc1 .Lsc_G_goz2
	s_mov_b32 s69, 0x100000

.Lsc_G_goz2:
	ds_read_b128 v[120:123], v11 offset:0
	ds_read_b128 v[124:127], v11 offset:16
	ds_read_b128 v[128:131], v11 offset:32
	ds_read_b128 v[132:135], v11 offset:48
	s_waitcnt lgkmcnt(0)
	v_pk_add_f32 v[120:121], v[120:121], v[122:123]
	v_pk_add_f32 v[124:125], v[124:125], v[126:127]
	v_pk_add_f32 v[120:121], v[120:121], v[124:125]
	v_add_f32_e32 v136, v120, v121
	v_pk_add_f32 v[128:129], v[128:129], v[130:131]
	v_pk_add_f32 v[132:133], v[132:133], v[134:135]
	v_pk_add_f32 v[128:129], v[128:129], v[132:133]
	v_add_f32_e32 v137, v128, v129
	global_store_dwordx2 v7, v[136:137], s[48:49]
	v_add_u32_e32 v7, s64, v7
	s_add_i32 s6, s6, 1
	v_add_u32_e32 v146, 1, v146
	s_waitcnt lgkmcnt(0)
	ds_write_b32 v145, v146
	s_sub_u32 s65, s6, 1
	ds_read_b128 v[148:151], v144
	s_waitcnt lgkmcnt(0)
	v_min_u32_e32 v148, v148, v149
	v_min3_u32 v148, v148, v150, v151
	s_nop 1
	v_readfirstlane_b32 s68, v148
	s_cmp_ge_u32 s68, s65
	s_cbranch_scc1 .Lsc_G_goz3
	s_mov_b32 s69, 0x100000
